# GEMM K-loops: load segments at prio 1 / MFMA blocks at prio 0 (raised before the barrier so an MFMA issues first); G4 and G5 K-loops without VALU: saddr LDS-DMA addressing, hoisted B read base
# speedup vs baseline: 1.0050x; 1.0049x over previous
.LBB0_230:
	s_add_u32 s33, s38, 0xfff00080
	s_addc_u32 s73, s39, -1
	s_add_i32 s75, 0, 0x10000
	s_cmp_eq_u32 s19, 60
	s_cselect_b32 s87, s1, s73
	s_cselect_b32 s86, s14, s33
	v_add_u32_e32 v114, s75, v119
	s_cselect_b32 s85, s15, s18
	s_cselect_b32 s84, s16, s17
	s_add_i32 s33, 0, 0x14000
	ds_read_b128 v[160:163], v114
	ds_read_b128 v[164:167], v114 offset:1024
	ds_read_b128 v[168:171], v114 offset:2048
	ds_read_b128 v[172:175], v114 offset:3072
	v_add_u32_e32 v114, s33, v119
	ds_read_b128 v[176:179], v114
	ds_read_b128 v[180:183], v114 offset:1024
	ds_read_b128 v[184:187], v114 offset:2048
	ds_read_b128 v[188:191], v114 offset:3072
	v_lshl_add_u64 v[202:203], s[38:39], 0, v[156:157]
	s_add_i32 m0, s7, 0xc000
	ds_read_b128 v[192:195], v141
	ds_read_b128 v[196:199], v141 offset:1024
	ds_read_b128 v[210:213], v141 offset:2048
	ds_read_b128 v[214:217], v141 offset:3072
	ds_read_b128 v[218:221], v141 offset:4096
	ds_read_b128 v[222:225], v141 offset:5120
	ds_read_b128 v[226:229], v141 offset:6144
	ds_read_b128 v[236:239], v141 offset:7168
	global_load_lds_dwordx4 v[202:203], off
	v_lshl_add_u64 v[202:203], s[38:39], 0, v[158:159]
	s_add_i32 m0, s7, 0xe000
	s_nop 0
	global_load_lds_dwordx4 v[202:203], off
	s_waitcnt vmcnt(8)
	s_waitcnt lgkmcnt(0)
	s_setprio 0
	s_barrier
	v_mfma_f32_16x16x32_bf16 v[132:135], v[160:163], v[192:195], v[132:135]
	v_mfma_f32_16x16x32_bf16 v[128:131], v[168:171], v[192:195], v[128:131]
	v_mfma_f32_16x16x32_bf16 v[124:127], v[160:163], v[210:213], v[124:127]
	v_mfma_f32_16x16x32_bf16 v[110:113], v[168:171], v[210:213], v[110:113]
	v_mfma_f32_16x16x32_bf16 v[102:105], v[160:163], v[218:221], v[102:105]
	v_mfma_f32_16x16x32_bf16 v[94:97], v[168:171], v[218:221], v[94:97]
	v_mfma_f32_16x16x32_bf16 v[86:89], v[160:163], v[226:229], v[86:89]
	v_mfma_f32_16x16x32_bf16 v[78:81], v[168:171], v[226:229], v[78:81]
	v_mfma_f32_16x16x32_bf16 v[132:135], v[164:167], v[196:199], v[132:135]
	v_mfma_f32_16x16x32_bf16 v[128:131], v[172:175], v[196:199], v[128:131]
	v_mfma_f32_16x16x32_bf16 v[124:127], v[164:167], v[214:217], v[124:127]
	v_mfma_f32_16x16x32_bf16 v[110:113], v[172:175], v[214:217], v[110:113]
	v_mfma_f32_16x16x32_bf16 v[102:105], v[164:167], v[222:225], v[102:105]
	v_mfma_f32_16x16x32_bf16 v[94:97], v[172:175], v[222:225], v[94:97]
	v_mfma_f32_16x16x32_bf16 v[86:89], v[164:167], v[236:239], v[86:89]
	v_mfma_f32_16x16x32_bf16 v[78:81], v[172:175], v[236:239], v[78:81]
	v_mfma_f32_16x16x32_bf16 v[120:123], v[176:179], v[192:195], v[120:123]
	v_mfma_f32_16x16x32_bf16 v[106:109], v[184:187], v[192:195], v[106:109]
	v_mfma_f32_16x16x32_bf16 v[98:101], v[176:179], v[210:213], v[98:101]
	v_mfma_f32_16x16x32_bf16 v[90:93], v[184:187], v[210:213], v[90:93]
	v_mfma_f32_16x16x32_bf16 v[82:85], v[176:179], v[218:221], v[82:85]
	v_mfma_f32_16x16x32_bf16 v[74:77], v[184:187], v[218:221], v[74:77]
	v_mfma_f32_16x16x32_bf16 v[70:73], v[176:179], v[226:229], v[70:73]
	v_mfma_f32_16x16x32_bf16 v[66:69], v[184:187], v[226:229], v[66:69]
	v_mfma_f32_16x16x32_bf16 v[120:123], v[180:183], v[196:199], v[120:123]
	v_mfma_f32_16x16x32_bf16 v[106:109], v[188:191], v[196:199], v[106:109]
	v_mfma_f32_16x16x32_bf16 v[98:101], v[180:183], v[214:217], v[98:101]
	v_mfma_f32_16x16x32_bf16 v[90:93], v[188:191], v[214:217], v[90:93]
	v_mfma_f32_16x16x32_bf16 v[82:85], v[180:183], v[222:225], v[82:85]
	v_mfma_f32_16x16x32_bf16 v[74:77], v[188:191], v[222:225], v[74:77]
	v_mfma_f32_16x16x32_bf16 v[70:73], v[180:183], v[236:239], v[70:73]
	v_mfma_f32_16x16x32_bf16 v[66:69], v[188:191], v[236:239], v[66:69]
	s_barrier
	s_setprio 1
	s_add_i32 s73, s75, s6
	v_lshl_add_u64 v[202:203], s[84:85], 0, v[148:149]
	s_mov_b32 m0, s73
	ds_read_b128 v[192:195], v141 offset:16384
	ds_read_b128 v[196:199], v141 offset:17408
	ds_read_b128 v[210:213], v141 offset:18432
	ds_read_b128 v[214:217], v141 offset:19456
	ds_read_b128 v[218:221], v141 offset:20480
	ds_read_b128 v[222:225], v141 offset:21504
	ds_read_b128 v[226:229], v141 offset:22528
	ds_read_b128 v[236:239], v141 offset:23552
	global_load_lds_dwordx4 v[202:203], off
	s_add_i32 m0, s73, 0x2000
	s_add_u32 vcc_lo, s84, 0x100000
	v_lshl_add_u64 v[240:241], s[84:85], 0, v[152:153]
	s_addc_u32 vcc_hi, s85, 0
	s_add_i32 s33, s33, s6
	global_load_lds_dwordx4 v[240:241], off
	v_lshl_add_u64 v[242:243], vcc, 0, v[148:149]
	s_mov_b32 m0, s33
	v_lshl_add_u64 v[244:245], s[86:87], 0, v[150:151]
	global_load_lds_dwordx4 v[242:243], off
	v_lshl_add_u64 v[242:243], vcc, 0, v[152:153]
	s_add_i32 m0, s33, 0x2000
	s_nop 0
	global_load_lds_dwordx4 v[242:243], off
	v_lshl_add_u64 v[242:243], s[86:87], 0, v[146:147]
	s_mov_b32 m0, s7
	s_nop 0
	global_load_lds_dwordx4 v[242:243], off
	s_mov_b32 m0, s8
	s_nop 0
	global_load_lds_dwordx4 v[244:245], off
	s_waitcnt vmcnt(8)
	s_waitcnt lgkmcnt(0)
	s_setprio 0
	s_barrier
	v_mfma_f32_16x16x32_bf16 v[62:65], v[160:163], v[192:195], v[62:65]
	v_mfma_f32_16x16x32_bf16 v[58:61], v[168:171], v[192:195], v[58:61]
	v_mfma_f32_16x16x32_bf16 v[54:57], v[160:163], v[210:213], v[54:57]
	v_mfma_f32_16x16x32_bf16 v[46:49], v[168:171], v[210:213], v[46:49]
	v_mfma_f32_16x16x32_bf16 v[38:41], v[160:163], v[218:221], v[38:41]
	v_mfma_f32_16x16x32_bf16 v[30:33], v[168:171], v[218:221], v[30:33]
	v_mfma_f32_16x16x32_bf16 v[22:25], v[160:163], v[226:229], v[22:25]
	v_mfma_f32_16x16x32_bf16 v[14:17], v[168:171], v[226:229], v[14:17]
	v_mfma_f32_16x16x32_bf16 v[62:65], v[164:167], v[196:199], v[62:65]
	v_mfma_f32_16x16x32_bf16 v[58:61], v[172:175], v[196:199], v[58:61]
	v_mfma_f32_16x16x32_bf16 v[54:57], v[164:167], v[214:217], v[54:57]
	v_mfma_f32_16x16x32_bf16 v[46:49], v[172:175], v[214:217], v[46:49]
	v_mfma_f32_16x16x32_bf16 v[38:41], v[164:167], v[222:225], v[38:41]
	v_mfma_f32_16x16x32_bf16 v[30:33], v[172:175], v[222:225], v[30:33]
	v_mfma_f32_16x16x32_bf16 v[22:25], v[164:167], v[236:239], v[22:25]
	v_mfma_f32_16x16x32_bf16 v[14:17], v[172:175], v[236:239], v[14:17]
	v_mfma_f32_16x16x32_bf16 v[50:53], v[176:179], v[192:195], v[50:53]
	v_mfma_f32_16x16x32_bf16 v[42:45], v[184:187], v[192:195], v[42:45]
	v_mfma_f32_16x16x32_bf16 v[34:37], v[176:179], v[210:213], v[34:37]
	v_mfma_f32_16x16x32_bf16 v[26:29], v[184:187], v[210:213], v[26:29]
	v_mfma_f32_16x16x32_bf16 v[18:21], v[176:179], v[218:221], v[18:21]
	v_mfma_f32_16x16x32_bf16 v[10:13], v[184:187], v[218:221], v[10:13]
	v_mfma_f32_16x16x32_bf16 v[6:9], v[176:179], v[226:229], v[6:9]
	v_mfma_f32_16x16x32_bf16 v[2:5], v[184:187], v[226:229], v[2:5]
	v_mfma_f32_16x16x32_bf16 v[50:53], v[180:183], v[196:199], v[50:53]
	v_mfma_f32_16x16x32_bf16 v[42:45], v[188:191], v[196:199], v[42:45]
	v_mfma_f32_16x16x32_bf16 v[34:37], v[180:183], v[214:217], v[34:37]
	v_mfma_f32_16x16x32_bf16 v[26:29], v[188:191], v[214:217], v[26:29]
	v_mfma_f32_16x16x32_bf16 v[18:21], v[180:183], v[222:225], v[18:21]
	v_mfma_f32_16x16x32_bf16 v[10:13], v[188:191], v[222:225], v[10:13]
	v_mfma_f32_16x16x32_bf16 v[6:9], v[180:183], v[236:239], v[6:9]
	v_mfma_f32_16x16x32_bf16 v[2:5], v[188:191], v[236:239], v[2:5]
	s_barrier
	s_setprio 1
	s_add_i32 s33, 0, 0x18000
	v_add_u32_e32 v114, s33, v119
	s_add_i32 s73, 0, 0x1c000
	ds_read_b128 v[160:163], v114
	ds_read_b128 v[164:167], v114 offset:1024
	ds_read_b128 v[168:171], v114 offset:2048
	ds_read_b128 v[172:175], v114 offset:3072
	v_add_u32_e32 v114, s73, v119
	ds_read_b128 v[176:179], v114
	ds_read_b128 v[180:183], v114 offset:1024
	ds_read_b128 v[184:187], v114 offset:2048
	ds_read_b128 v[188:191], v114 offset:3072
	s_add_u32 s86, s86, 0x100000
	s_addc_u32 s87, s87, 0
	s_mov_b32 m0, s9
	v_lshl_add_u64 v[246:247], s[86:87], 0, v[146:147]
	ds_read_b128 v[192:195], v141 offset:32768
	ds_read_b128 v[196:199], v141 offset:33792
	ds_read_b128 v[210:213], v141 offset:34816
	ds_read_b128 v[214:217], v141 offset:35840
	ds_read_b128 v[218:221], v141 offset:36864
	ds_read_b128 v[222:225], v141 offset:37888
	ds_read_b128 v[226:229], v141 offset:38912
	ds_read_b128 v[236:239], v141 offset:39936
	global_load_lds_dwordx4 v[246:247], off
	v_lshl_add_u64 v[246:247], s[86:87], 0, v[150:151]
	s_mov_b32 m0, s10
	s_nop 0
	global_load_lds_dwordx4 v[246:247], off
	s_waitcnt vmcnt(8)
	s_waitcnt lgkmcnt(0)
	s_setprio 0
	s_barrier
	v_mfma_f32_16x16x32_bf16 v[132:135], v[160:163], v[192:195], v[132:135]
	v_mfma_f32_16x16x32_bf16 v[128:131], v[168:171], v[192:195], v[128:131]
	v_mfma_f32_16x16x32_bf16 v[124:127], v[160:163], v[210:213], v[124:127]
	v_mfma_f32_16x16x32_bf16 v[110:113], v[168:171], v[210:213], v[110:113]
	v_mfma_f32_16x16x32_bf16 v[102:105], v[160:163], v[218:221], v[102:105]
	v_mfma_f32_16x16x32_bf16 v[94:97], v[168:171], v[218:221], v[94:97]
	v_mfma_f32_16x16x32_bf16 v[86:89], v[160:163], v[226:229], v[86:89]
	v_mfma_f32_16x16x32_bf16 v[78:81], v[168:171], v[226:229], v[78:81]
	v_mfma_f32_16x16x32_bf16 v[132:135], v[164:167], v[196:199], v[132:135]
	v_mfma_f32_16x16x32_bf16 v[128:131], v[172:175], v[196:199], v[128:131]
	v_mfma_f32_16x16x32_bf16 v[124:127], v[164:167], v[214:217], v[124:127]
	v_mfma_f32_16x16x32_bf16 v[110:113], v[172:175], v[214:217], v[110:113]
	v_mfma_f32_16x16x32_bf16 v[102:105], v[164:167], v[222:225], v[102:105]
	v_mfma_f32_16x16x32_bf16 v[94:97], v[172:175], v[222:225], v[94:97]
	v_mfma_f32_16x16x32_bf16 v[86:89], v[164:167], v[236:239], v[86:89]
	v_mfma_f32_16x16x32_bf16 v[78:81], v[172:175], v[236:239], v[78:81]
	v_mfma_f32_16x16x32_bf16 v[120:123], v[176:179], v[192:195], v[120:123]
	v_mfma_f32_16x16x32_bf16 v[106:109], v[184:187], v[192:195], v[106:109]
	v_mfma_f32_16x16x32_bf16 v[98:101], v[176:179], v[210:213], v[98:101]
	v_mfma_f32_16x16x32_bf16 v[90:93], v[184:187], v[210:213], v[90:93]
	v_mfma_f32_16x16x32_bf16 v[82:85], v[176:179], v[218:221], v[82:85]
	v_mfma_f32_16x16x32_bf16 v[74:77], v[184:187], v[218:221], v[74:77]
	v_mfma_f32_16x16x32_bf16 v[70:73], v[176:179], v[226:229], v[70:73]
	v_mfma_f32_16x16x32_bf16 v[66:69], v[184:187], v[226:229], v[66:69]
	v_mfma_f32_16x16x32_bf16 v[120:123], v[180:183], v[196:199], v[120:123]
	v_mfma_f32_16x16x32_bf16 v[106:109], v[188:191], v[196:199], v[106:109]
	v_mfma_f32_16x16x32_bf16 v[98:101], v[180:183], v[214:217], v[98:101]
	v_mfma_f32_16x16x32_bf16 v[90:93], v[188:191], v[214:217], v[90:93]
	v_mfma_f32_16x16x32_bf16 v[82:85], v[180:183], v[222:225], v[82:85]
	v_mfma_f32_16x16x32_bf16 v[74:77], v[188:191], v[222:225], v[74:77]
	v_mfma_f32_16x16x32_bf16 v[70:73], v[180:183], v[236:239], v[70:73]
	v_mfma_f32_16x16x32_bf16 v[66:69], v[188:191], v[236:239], v[66:69]
	s_barrier
	s_setprio 1
	s_add_i32 s33, s33, s6
	v_lshl_add_u64 v[202:203], v[202:203], 0, s[20:21]
	s_mov_b32 m0, s33
	ds_read_b128 v[192:195], v141 offset:49152
	ds_read_b128 v[196:199], v141 offset:50176
	ds_read_b128 v[210:213], v141 offset:51200
	ds_read_b128 v[214:217], v141 offset:52224
	ds_read_b128 v[218:221], v141 offset:53248
	ds_read_b128 v[222:225], v141 offset:54272
	ds_read_b128 v[226:229], v141 offset:55296
	ds_read_b128 v[236:239], v141 offset:56320
	global_load_lds_dwordx4 v[202:203], off
	s_add_i32 m0, s33, 0x2000
	s_add_u32 s84, s84, 0x100080
	v_lshl_add_u64 v[202:203], v[240:241], 0, s[20:21]
	s_addc_u32 s85, s85, 0
	s_add_i32 s33, s73, s6
	global_load_lds_dwordx4 v[202:203], off
	v_lshl_add_u64 v[202:203], s[84:85], 0, v[148:149]
	s_mov_b32 m0, s33
	s_nop 0
	global_load_lds_dwordx4 v[202:203], off
	v_lshl_add_u64 v[202:203], s[84:85], 0, v[152:153]
	s_add_i32 m0, s33, 0x2000
	s_nop 0
	global_load_lds_dwordx4 v[202:203], off
	v_lshl_add_u64 v[202:203], v[242:243], 0, s[20:21]
	s_mov_b32 m0, s11
	s_nop 0
	global_load_lds_dwordx4 v[202:203], off
	v_lshl_add_u64 v[202:203], v[244:245], 0, s[20:21]
	s_mov_b32 m0, s12
	s_nop 0
	global_load_lds_dwordx4 v[202:203], off
	s_waitcnt vmcnt(8)
	s_waitcnt lgkmcnt(0)
	s_setprio 0
	s_barrier
	v_mfma_f32_16x16x32_bf16 v[62:65], v[160:163], v[192:195], v[62:65]
	v_mfma_f32_16x16x32_bf16 v[58:61], v[168:171], v[192:195], v[58:61]
	v_mfma_f32_16x16x32_bf16 v[54:57], v[160:163], v[210:213], v[54:57]
	v_mfma_f32_16x16x32_bf16 v[46:49], v[168:171], v[210:213], v[46:49]
	v_mfma_f32_16x16x32_bf16 v[38:41], v[160:163], v[218:221], v[38:41]
	v_mfma_f32_16x16x32_bf16 v[30:33], v[168:171], v[218:221], v[30:33]
	v_mfma_f32_16x16x32_bf16 v[22:25], v[160:163], v[226:229], v[22:25]
	v_mfma_f32_16x16x32_bf16 v[14:17], v[168:171], v[226:229], v[14:17]
	v_mfma_f32_16x16x32_bf16 v[62:65], v[164:167], v[196:199], v[62:65]
	v_mfma_f32_16x16x32_bf16 v[58:61], v[172:175], v[196:199], v[58:61]
	v_mfma_f32_16x16x32_bf16 v[54:57], v[164:167], v[214:217], v[54:57]
	v_mfma_f32_16x16x32_bf16 v[46:49], v[172:175], v[214:217], v[46:49]
	v_mfma_f32_16x16x32_bf16 v[38:41], v[164:167], v[222:225], v[38:41]
	v_mfma_f32_16x16x32_bf16 v[30:33], v[172:175], v[222:225], v[30:33]
	v_mfma_f32_16x16x32_bf16 v[22:25], v[164:167], v[236:239], v[22:25]
	v_mfma_f32_16x16x32_bf16 v[14:17], v[172:175], v[236:239], v[14:17]
	v_mfma_f32_16x16x32_bf16 v[50:53], v[176:179], v[192:195], v[50:53]
	v_mfma_f32_16x16x32_bf16 v[42:45], v[184:187], v[192:195], v[42:45]
	v_mfma_f32_16x16x32_bf16 v[34:37], v[176:179], v[210:213], v[34:37]
	v_mfma_f32_16x16x32_bf16 v[26:29], v[184:187], v[210:213], v[26:29]
	v_mfma_f32_16x16x32_bf16 v[18:21], v[176:179], v[218:221], v[18:21]
	v_mfma_f32_16x16x32_bf16 v[10:13], v[184:187], v[218:221], v[10:13]
	v_mfma_f32_16x16x32_bf16 v[6:9], v[176:179], v[226:229], v[6:9]
	v_mfma_f32_16x16x32_bf16 v[2:5], v[184:187], v[226:229], v[2:5]
	v_mfma_f32_16x16x32_bf16 v[50:53], v[180:183], v[196:199], v[50:53]
	v_mfma_f32_16x16x32_bf16 v[42:45], v[188:191], v[196:199], v[42:45]
	v_mfma_f32_16x16x32_bf16 v[34:37], v[180:183], v[214:217], v[34:37]
	v_mfma_f32_16x16x32_bf16 v[26:29], v[188:191], v[214:217], v[26:29]
	v_mfma_f32_16x16x32_bf16 v[18:21], v[180:183], v[222:225], v[18:21]
	v_mfma_f32_16x16x32_bf16 v[10:13], v[188:191], v[222:225], v[10:13]
	v_mfma_f32_16x16x32_bf16 v[6:9], v[180:183], v[236:239], v[6:9]
	v_mfma_f32_16x16x32_bf16 v[2:5], v[188:191], v[236:239], v[2:5]
	s_barrier
	s_setprio 1
	s_add_i32 s19, s19, 2
	s_add_u32 s38, s38, 0x100
	s_addc_u32 s39, s39, 0
	s_add_u32 s17, s17, 0x100
	s_addc_u32 s18, s18, 0
	s_cmp_gt_u32 s19, 61
	s_cbranch_scc0 .LBB0_230
	s_setprio 0
	s_and_b64 vcc, exec, s[30:31]
	s_cbranch_vccz .LBB0_233
	s_barrier

.LBB0_460:
	s_add_u32 s10, s24, 0xfffc0080
	s_addc_u32 s11, s25, -1
	s_add_i32 s12, 0, 0x10000
	s_cmp_eq_u32 s9, 12
	s_cselect_b32 s31, s1, s11
	s_cselect_b32 s30, s4, s10
	v_add_u32_e32 v114, s12, v119
	s_cselect_b32 s27, s5, s8
	s_cselect_b32 s26, s6, s7
	s_add_i32 s13, 0, 0x14000
	ds_read_b128 v[136:139], v114
	ds_read_b128 v[140:143], v114 offset:1024
	ds_read_b128 v[144:147], v114 offset:2048
	ds_read_b128 v[148:151], v114 offset:3072
	v_add_u32_e32 v114, s13, v119
	ds_read_b128 v[182:185], v114
	ds_read_b128 v[186:189], v114 offset:1024
	ds_read_b128 v[190:193], v114 offset:2048
	ds_read_b128 v[194:197], v114 offset:3072
	v_lshl_add_u64 v[170:171], s[24:25], 0, v[166:167]
	s_add_i32 m0, s53, 0xc000
	ds_read_b128 v[210:213], v181
	ds_read_b128 v[214:217], v181 offset:1024
	ds_read_b128 v[218:221], v181 offset:2048
	ds_read_b128 v[222:225], v181 offset:3072
	ds_read_b128 v[226:229], v181 offset:4096
	ds_read_b128 v[236:239], v181 offset:5120
	ds_read_b128 v[240:243], v181 offset:6144
	ds_read_b128 v[244:247], v181 offset:7168
	global_load_lds_dwordx4 v[170:171], off
	v_lshl_add_u64 v[170:171], s[24:25], 0, v[168:169]
	s_add_i32 m0, s53, 0xe000
	s_nop 0
	global_load_lds_dwordx4 v[170:171], off
	s_waitcnt vmcnt(8)
	s_waitcnt lgkmcnt(0)
	s_setprio 0
	s_barrier
	v_mfma_f32_16x16x32_bf16 v[132:135], v[136:139], v[210:213], v[132:135]
	v_mfma_f32_16x16x32_bf16 v[128:131], v[144:147], v[210:213], v[128:131]
	v_mfma_f32_16x16x32_bf16 v[120:123], v[136:139], v[218:221], v[120:123]
	v_mfma_f32_16x16x32_bf16 v[106:109], v[144:147], v[218:221], v[106:109]
	v_mfma_f32_16x16x32_bf16 v[98:101], v[136:139], v[226:229], v[98:101]
	v_mfma_f32_16x16x32_bf16 v[90:93], v[144:147], v[226:229], v[90:93]
	v_mfma_f32_16x16x32_bf16 v[82:85], v[136:139], v[240:243], v[82:85]
	v_mfma_f32_16x16x32_bf16 v[74:77], v[144:147], v[240:243], v[74:77]
	v_mfma_f32_16x16x32_bf16 v[132:135], v[140:143], v[214:217], v[132:135]
	v_mfma_f32_16x16x32_bf16 v[128:131], v[148:151], v[214:217], v[128:131]
	v_mfma_f32_16x16x32_bf16 v[120:123], v[140:143], v[222:225], v[120:123]
	v_mfma_f32_16x16x32_bf16 v[106:109], v[148:151], v[222:225], v[106:109]
	v_mfma_f32_16x16x32_bf16 v[98:101], v[140:143], v[236:239], v[98:101]
	v_mfma_f32_16x16x32_bf16 v[90:93], v[148:151], v[236:239], v[90:93]
	v_mfma_f32_16x16x32_bf16 v[82:85], v[140:143], v[244:247], v[82:85]
	v_mfma_f32_16x16x32_bf16 v[74:77], v[148:151], v[244:247], v[74:77]
	v_mfma_f32_16x16x32_bf16 v[124:127], v[182:185], v[210:213], v[124:127]
	v_mfma_f32_16x16x32_bf16 v[110:113], v[190:193], v[210:213], v[110:113]
	v_mfma_f32_16x16x32_bf16 v[102:105], v[182:185], v[218:221], v[102:105]
	v_mfma_f32_16x16x32_bf16 v[94:97], v[190:193], v[218:221], v[94:97]
	v_mfma_f32_16x16x32_bf16 v[86:89], v[182:185], v[226:229], v[86:89]
	v_mfma_f32_16x16x32_bf16 v[78:81], v[190:193], v[226:229], v[78:81]
	v_mfma_f32_16x16x32_bf16 v[70:73], v[182:185], v[240:243], v[70:73]
	v_mfma_f32_16x16x32_bf16 v[66:69], v[190:193], v[240:243], v[66:69]
	v_mfma_f32_16x16x32_bf16 v[124:127], v[186:189], v[214:217], v[124:127]
	v_mfma_f32_16x16x32_bf16 v[110:113], v[194:197], v[214:217], v[110:113]
	v_mfma_f32_16x16x32_bf16 v[102:105], v[186:189], v[222:225], v[102:105]
	v_mfma_f32_16x16x32_bf16 v[94:97], v[194:197], v[222:225], v[94:97]
	v_mfma_f32_16x16x32_bf16 v[86:89], v[186:189], v[236:239], v[86:89]
	v_mfma_f32_16x16x32_bf16 v[78:81], v[194:197], v[236:239], v[78:81]
	v_mfma_f32_16x16x32_bf16 v[70:73], v[186:189], v[244:247], v[70:73]
	v_mfma_f32_16x16x32_bf16 v[66:69], v[194:197], v[244:247], v[66:69]
	s_barrier
	s_setprio 1
	s_add_i32 s10, s12, s58
	v_lshl_add_u64 v[170:171], s[26:27], 0, v[152:153]
	s_mov_b32 m0, s10
	ds_read_b128 v[210:213], v181 offset:16384
	ds_read_b128 v[214:217], v181 offset:17408
	ds_read_b128 v[218:221], v181 offset:18432
	ds_read_b128 v[222:225], v181 offset:19456
	ds_read_b128 v[226:229], v181 offset:20480
	ds_read_b128 v[236:239], v181 offset:21504
	ds_read_b128 v[240:243], v181 offset:22528
	ds_read_b128 v[244:247], v181 offset:23552
	global_load_lds_dwordx4 v[170:171], off
	s_add_i32 m0, s10, 0x2000
	s_add_u32 s10, s26, 0x40000
	v_lshl_add_u64 v[198:199], s[26:27], 0, v[156:157]
	s_addc_u32 s11, s27, 0
	s_add_i32 s12, s13, s58
	global_load_lds_dwordx4 v[198:199], off
	v_lshl_add_u64 v[202:203], s[10:11], 0, v[152:153]
	s_mov_b32 m0, s12
	v_lshl_add_u64 v[248:249], s[30:31], 0, v[154:155]
	global_load_lds_dwordx4 v[202:203], off
	v_lshl_add_u64 v[202:203], s[10:11], 0, v[156:157]
	s_add_i32 m0, s12, 0x2000
	s_nop 0
	global_load_lds_dwordx4 v[202:203], off
	v_lshl_add_u64 v[202:203], s[30:31], 0, v[116:117]
	s_mov_b32 m0, s53
	s_nop 0
	global_load_lds_dwordx4 v[202:203], off
	s_mov_b32 m0, s59
	s_nop 0
	global_load_lds_dwordx4 v[248:249], off
	s_waitcnt vmcnt(8)
	s_waitcnt lgkmcnt(0)
	s_setprio 0
	s_barrier
	v_mfma_f32_16x16x32_bf16 v[62:65], v[136:139], v[210:213], v[62:65]
	v_mfma_f32_16x16x32_bf16 v[58:61], v[144:147], v[210:213], v[58:61]
	v_mfma_f32_16x16x32_bf16 v[50:53], v[136:139], v[218:221], v[50:53]
	v_mfma_f32_16x16x32_bf16 v[42:45], v[144:147], v[218:221], v[42:45]
	v_mfma_f32_16x16x32_bf16 v[34:37], v[136:139], v[226:229], v[34:37]
	v_mfma_f32_16x16x32_bf16 v[26:29], v[144:147], v[226:229], v[26:29]
	v_mfma_f32_16x16x32_bf16 v[14:17], v[136:139], v[240:243], v[14:17]
	v_mfma_f32_16x16x32_bf16 v[10:13], v[144:147], v[240:243], v[10:13]
	v_mfma_f32_16x16x32_bf16 v[62:65], v[140:143], v[214:217], v[62:65]
	v_mfma_f32_16x16x32_bf16 v[58:61], v[148:151], v[214:217], v[58:61]
	v_mfma_f32_16x16x32_bf16 v[50:53], v[140:143], v[222:225], v[50:53]
	v_mfma_f32_16x16x32_bf16 v[42:45], v[148:151], v[222:225], v[42:45]
	v_mfma_f32_16x16x32_bf16 v[34:37], v[140:143], v[236:239], v[34:37]
	v_mfma_f32_16x16x32_bf16 v[26:29], v[148:151], v[236:239], v[26:29]
	v_mfma_f32_16x16x32_bf16 v[14:17], v[140:143], v[244:247], v[14:17]
	v_mfma_f32_16x16x32_bf16 v[10:13], v[148:151], v[244:247], v[10:13]
	v_mfma_f32_16x16x32_bf16 v[54:57], v[182:185], v[210:213], v[54:57]
	v_mfma_f32_16x16x32_bf16 v[46:49], v[190:193], v[210:213], v[46:49]
	v_mfma_f32_16x16x32_bf16 v[38:41], v[182:185], v[218:221], v[38:41]
	v_mfma_f32_16x16x32_bf16 v[30:33], v[190:193], v[218:221], v[30:33]
	v_mfma_f32_16x16x32_bf16 v[22:25], v[182:185], v[226:229], v[22:25]
	v_mfma_f32_16x16x32_bf16 v[18:21], v[190:193], v[226:229], v[18:21]
	v_mfma_f32_16x16x32_bf16 v[6:9], v[182:185], v[240:243], v[6:9]
	v_mfma_f32_16x16x32_bf16 v[2:5], v[190:193], v[240:243], v[2:5]
	v_mfma_f32_16x16x32_bf16 v[54:57], v[186:189], v[214:217], v[54:57]
	v_mfma_f32_16x16x32_bf16 v[46:49], v[194:197], v[214:217], v[46:49]
	v_mfma_f32_16x16x32_bf16 v[38:41], v[186:189], v[222:225], v[38:41]
	v_mfma_f32_16x16x32_bf16 v[30:33], v[194:197], v[222:225], v[30:33]
	v_mfma_f32_16x16x32_bf16 v[22:25], v[186:189], v[236:239], v[22:25]
	v_mfma_f32_16x16x32_bf16 v[18:21], v[194:197], v[236:239], v[18:21]
	v_mfma_f32_16x16x32_bf16 v[6:9], v[186:189], v[244:247], v[6:9]
	v_mfma_f32_16x16x32_bf16 v[2:5], v[194:197], v[244:247], v[2:5]
	s_barrier
	s_setprio 1
	s_add_i32 s12, 0, 0x18000
	v_add_u32_e32 v114, s12, v119
	s_add_i32 s13, 0, 0x1c000
	ds_read_b128 v[136:139], v114
	ds_read_b128 v[140:143], v114 offset:1024
	ds_read_b128 v[144:147], v114 offset:2048
	ds_read_b128 v[148:151], v114 offset:3072
	v_add_u32_e32 v114, s13, v119
	ds_read_b128 v[182:185], v114
	ds_read_b128 v[186:189], v114 offset:1024
	ds_read_b128 v[190:193], v114 offset:2048
	ds_read_b128 v[194:197], v114 offset:3072
	s_add_u32 s10, s30, 0x40000
	s_addc_u32 s11, s31, 0
	s_mov_b32 m0, s60
	v_lshl_add_u64 v[250:251], s[10:11], 0, v[116:117]
	ds_read_b128 v[210:213], v181 offset:32768
	ds_read_b128 v[214:217], v181 offset:33792
	ds_read_b128 v[218:221], v181 offset:34816
	ds_read_b128 v[222:225], v181 offset:35840
	ds_read_b128 v[226:229], v181 offset:36864
	ds_read_b128 v[236:239], v181 offset:37888
	ds_read_b128 v[240:243], v181 offset:38912
	ds_read_b128 v[244:247], v181 offset:39936
	global_load_lds_dwordx4 v[250:251], off
	v_lshl_add_u64 v[250:251], s[10:11], 0, v[154:155]
	s_mov_b32 m0, s61
	s_nop 0
	global_load_lds_dwordx4 v[250:251], off
	s_waitcnt vmcnt(8)
	s_waitcnt lgkmcnt(0)
	s_setprio 0
	s_barrier
	v_mfma_f32_16x16x32_bf16 v[132:135], v[136:139], v[210:213], v[132:135]
	v_mfma_f32_16x16x32_bf16 v[128:131], v[144:147], v[210:213], v[128:131]
	v_mfma_f32_16x16x32_bf16 v[120:123], v[136:139], v[218:221], v[120:123]
	v_mfma_f32_16x16x32_bf16 v[106:109], v[144:147], v[218:221], v[106:109]
	v_mfma_f32_16x16x32_bf16 v[98:101], v[136:139], v[226:229], v[98:101]
	v_mfma_f32_16x16x32_bf16 v[90:93], v[144:147], v[226:229], v[90:93]
	v_mfma_f32_16x16x32_bf16 v[82:85], v[136:139], v[240:243], v[82:85]
	v_mfma_f32_16x16x32_bf16 v[74:77], v[144:147], v[240:243], v[74:77]
	v_mfma_f32_16x16x32_bf16 v[132:135], v[140:143], v[214:217], v[132:135]
	v_mfma_f32_16x16x32_bf16 v[128:131], v[148:151], v[214:217], v[128:131]
	v_mfma_f32_16x16x32_bf16 v[120:123], v[140:143], v[222:225], v[120:123]
	v_mfma_f32_16x16x32_bf16 v[106:109], v[148:151], v[222:225], v[106:109]
	v_mfma_f32_16x16x32_bf16 v[98:101], v[140:143], v[236:239], v[98:101]
	v_mfma_f32_16x16x32_bf16 v[90:93], v[148:151], v[236:239], v[90:93]
	v_mfma_f32_16x16x32_bf16 v[82:85], v[140:143], v[244:247], v[82:85]
	v_mfma_f32_16x16x32_bf16 v[74:77], v[148:151], v[244:247], v[74:77]
	v_mfma_f32_16x16x32_bf16 v[124:127], v[182:185], v[210:213], v[124:127]
	v_mfma_f32_16x16x32_bf16 v[110:113], v[190:193], v[210:213], v[110:113]
	v_mfma_f32_16x16x32_bf16 v[102:105], v[182:185], v[218:221], v[102:105]
	v_mfma_f32_16x16x32_bf16 v[94:97], v[190:193], v[218:221], v[94:97]
	v_mfma_f32_16x16x32_bf16 v[86:89], v[182:185], v[226:229], v[86:89]
	v_mfma_f32_16x16x32_bf16 v[78:81], v[190:193], v[226:229], v[78:81]
	v_mfma_f32_16x16x32_bf16 v[70:73], v[182:185], v[240:243], v[70:73]
	v_mfma_f32_16x16x32_bf16 v[66:69], v[190:193], v[240:243], v[66:69]
	v_mfma_f32_16x16x32_bf16 v[124:127], v[186:189], v[214:217], v[124:127]
	v_mfma_f32_16x16x32_bf16 v[110:113], v[194:197], v[214:217], v[110:113]
	v_mfma_f32_16x16x32_bf16 v[102:105], v[186:189], v[222:225], v[102:105]
	v_mfma_f32_16x16x32_bf16 v[94:97], v[194:197], v[222:225], v[94:97]
	v_mfma_f32_16x16x32_bf16 v[86:89], v[186:189], v[236:239], v[86:89]
	v_mfma_f32_16x16x32_bf16 v[78:81], v[194:197], v[236:239], v[78:81]
	v_mfma_f32_16x16x32_bf16 v[70:73], v[186:189], v[244:247], v[70:73]
	v_mfma_f32_16x16x32_bf16 v[66:69], v[194:197], v[244:247], v[66:69]
	s_barrier
	s_setprio 1
	s_add_i32 s10, s12, s58
	v_lshl_add_u64 v[170:171], v[170:171], 0, s[20:21]
	s_mov_b32 m0, s10
	ds_read_b128 v[210:213], v181 offset:49152
	ds_read_b128 v[214:217], v181 offset:50176
	ds_read_b128 v[218:221], v181 offset:51200
	ds_read_b128 v[222:225], v181 offset:52224
	ds_read_b128 v[226:229], v181 offset:53248
	ds_read_b128 v[236:239], v181 offset:54272
	ds_read_b128 v[240:243], v181 offset:55296
	ds_read_b128 v[244:247], v181 offset:56320
	global_load_lds_dwordx4 v[170:171], off
	s_add_i32 m0, s10, 0x2000
	s_add_u32 s10, s26, 0x40080
	v_lshl_add_u64 v[170:171], v[198:199], 0, s[20:21]
	s_addc_u32 s11, s27, 0
	s_add_i32 s12, s13, s58
	global_load_lds_dwordx4 v[170:171], off
	v_lshl_add_u64 v[170:171], s[10:11], 0, v[152:153]
	s_mov_b32 m0, s12
	s_nop 0
	global_load_lds_dwordx4 v[170:171], off
	v_lshl_add_u64 v[170:171], s[10:11], 0, v[156:157]
	s_add_i32 m0, s12, 0x2000
	s_nop 0
	global_load_lds_dwordx4 v[170:171], off
	v_lshl_add_u64 v[170:171], v[202:203], 0, s[20:21]
	s_mov_b32 m0, s62
	s_nop 0
	global_load_lds_dwordx4 v[170:171], off
	v_lshl_add_u64 v[170:171], v[248:249], 0, s[20:21]
	s_mov_b32 m0, s63
	s_nop 0
	global_load_lds_dwordx4 v[170:171], off
	s_waitcnt vmcnt(8)
	s_waitcnt lgkmcnt(0)
	s_setprio 0
	s_barrier
	v_mfma_f32_16x16x32_bf16 v[62:65], v[136:139], v[210:213], v[62:65]
	v_mfma_f32_16x16x32_bf16 v[58:61], v[144:147], v[210:213], v[58:61]
	v_mfma_f32_16x16x32_bf16 v[50:53], v[136:139], v[218:221], v[50:53]
	v_mfma_f32_16x16x32_bf16 v[42:45], v[144:147], v[218:221], v[42:45]
	v_mfma_f32_16x16x32_bf16 v[34:37], v[136:139], v[226:229], v[34:37]
	v_mfma_f32_16x16x32_bf16 v[26:29], v[144:147], v[226:229], v[26:29]
	v_mfma_f32_16x16x32_bf16 v[14:17], v[136:139], v[240:243], v[14:17]
	v_mfma_f32_16x16x32_bf16 v[10:13], v[144:147], v[240:243], v[10:13]
	v_mfma_f32_16x16x32_bf16 v[62:65], v[140:143], v[214:217], v[62:65]
	v_mfma_f32_16x16x32_bf16 v[58:61], v[148:151], v[214:217], v[58:61]
	v_mfma_f32_16x16x32_bf16 v[50:53], v[140:143], v[222:225], v[50:53]
	v_mfma_f32_16x16x32_bf16 v[42:45], v[148:151], v[222:225], v[42:45]
	v_mfma_f32_16x16x32_bf16 v[34:37], v[140:143], v[236:239], v[34:37]
	v_mfma_f32_16x16x32_bf16 v[26:29], v[148:151], v[236:239], v[26:29]
	v_mfma_f32_16x16x32_bf16 v[14:17], v[140:143], v[244:247], v[14:17]
	v_mfma_f32_16x16x32_bf16 v[10:13], v[148:151], v[244:247], v[10:13]
	v_mfma_f32_16x16x32_bf16 v[54:57], v[182:185], v[210:213], v[54:57]
	v_mfma_f32_16x16x32_bf16 v[46:49], v[190:193], v[210:213], v[46:49]
	v_mfma_f32_16x16x32_bf16 v[38:41], v[182:185], v[218:221], v[38:41]
	v_mfma_f32_16x16x32_bf16 v[30:33], v[190:193], v[218:221], v[30:33]
	v_mfma_f32_16x16x32_bf16 v[22:25], v[182:185], v[226:229], v[22:25]
	v_mfma_f32_16x16x32_bf16 v[18:21], v[190:193], v[226:229], v[18:21]
	v_mfma_f32_16x16x32_bf16 v[6:9], v[182:185], v[240:243], v[6:9]
	v_mfma_f32_16x16x32_bf16 v[2:5], v[190:193], v[240:243], v[2:5]
	v_mfma_f32_16x16x32_bf16 v[54:57], v[186:189], v[214:217], v[54:57]
	v_mfma_f32_16x16x32_bf16 v[46:49], v[194:197], v[214:217], v[46:49]
	v_mfma_f32_16x16x32_bf16 v[38:41], v[186:189], v[222:225], v[38:41]
	v_mfma_f32_16x16x32_bf16 v[30:33], v[194:197], v[222:225], v[30:33]
	v_mfma_f32_16x16x32_bf16 v[22:25], v[186:189], v[236:239], v[22:25]
	v_mfma_f32_16x16x32_bf16 v[18:21], v[194:197], v[236:239], v[18:21]
	v_mfma_f32_16x16x32_bf16 v[6:9], v[186:189], v[244:247], v[6:9]
	v_mfma_f32_16x16x32_bf16 v[2:5], v[194:197], v[244:247], v[2:5]
	s_barrier
	s_setprio 1
	s_add_i32 s9, s9, 2
	s_add_u32 s24, s24, 0x100
	s_addc_u32 s25, s25, 0
	s_add_u32 s7, s7, 0x100
	s_addc_u32 s8, s8, 0
	s_cmp_gt_u32 s9, 13
	s_cbranch_scc0 .LBB0_460
	s_setprio 0
	s_and_b64 vcc, exec, s[22:23]
	s_cbranch_vccz .LBB0_463
	s_barrier

.LBB0_514:
	s_add_u32 s10, s48, 0xfffe0080
	s_addc_u32 s11, s49, -1
	s_add_i32 s12, 0, 0x10000
	s_cmp_eq_u32 s9, 4
	s_cselect_b32 s53, s1, s11
	s_cselect_b32 s52, s4, s10
	v_add_u32_e32 v114, s12, v119
	s_cselect_b32 s51, s5, s8
	s_cselect_b32 s50, s6, s7
	s_add_i32 s13, 0, 0x14000
	ds_read_b128 v[136:139], v114
	ds_read_b128 v[140:143], v114 offset:1024
	ds_read_b128 v[158:161], v114 offset:2048
	ds_read_b128 v[162:165], v114 offset:3072
	v_add_u32_e32 v114, s13, v119
	ds_read_b128 v[170:173], v114
	ds_read_b128 v[174:177], v114 offset:1024
	ds_read_b128 v[178:181], v114 offset:2048
	ds_read_b128 v[182:185], v114 offset:3072
	v_lshl_add_u64 v[166:167], s[48:49], 0, v[154:155]
	s_add_i32 m0, s31, 0xc000
	ds_read_b128 v[186:189], v169
	ds_read_b128 v[190:193], v169 offset:1024
	ds_read_b128 v[194:197], v169 offset:2048
	ds_read_b128 v[210:213], v169 offset:3072
	ds_read_b128 v[214:217], v169 offset:4096
	ds_read_b128 v[218:221], v169 offset:5120
	ds_read_b128 v[222:225], v169 offset:6144
	ds_read_b128 v[226:229], v169 offset:7168
	global_load_lds_dwordx4 v[166:167], off
	v_lshl_add_u64 v[166:167], s[48:49], 0, v[156:157]
	s_add_i32 m0, s31, 0xe000
	s_nop 0
	global_load_lds_dwordx4 v[166:167], off
	s_waitcnt vmcnt(8)
	s_waitcnt lgkmcnt(0)
	s_setprio 0
	s_barrier
	v_mfma_f32_16x16x32_bf16 v[132:135], v[136:139], v[186:189], v[132:135]
	v_mfma_f32_16x16x32_bf16 v[128:131], v[158:161], v[186:189], v[128:131]
	v_mfma_f32_16x16x32_bf16 v[110:113], v[136:139], v[194:197], v[110:113]
	v_mfma_f32_16x16x32_bf16 v[106:109], v[158:161], v[194:197], v[106:109]
	v_mfma_f32_16x16x32_bf16 v[94:97], v[136:139], v[214:217], v[94:97]
	v_mfma_f32_16x16x32_bf16 v[90:93], v[158:161], v[214:217], v[90:93]
	v_mfma_f32_16x16x32_bf16 v[78:81], v[136:139], v[222:225], v[78:81]
	v_mfma_f32_16x16x32_bf16 v[74:77], v[158:161], v[222:225], v[74:77]
	v_mfma_f32_16x16x32_bf16 v[132:135], v[140:143], v[190:193], v[132:135]
	v_mfma_f32_16x16x32_bf16 v[128:131], v[162:165], v[190:193], v[128:131]
	v_mfma_f32_16x16x32_bf16 v[110:113], v[140:143], v[210:213], v[110:113]
	v_mfma_f32_16x16x32_bf16 v[106:109], v[162:165], v[210:213], v[106:109]
	v_mfma_f32_16x16x32_bf16 v[94:97], v[140:143], v[218:221], v[94:97]
	v_mfma_f32_16x16x32_bf16 v[90:93], v[162:165], v[218:221], v[90:93]
	v_mfma_f32_16x16x32_bf16 v[78:81], v[140:143], v[226:229], v[78:81]
	v_mfma_f32_16x16x32_bf16 v[74:77], v[162:165], v[226:229], v[74:77]
	v_mfma_f32_16x16x32_bf16 v[124:127], v[170:173], v[186:189], v[124:127]
	v_mfma_f32_16x16x32_bf16 v[120:123], v[178:181], v[186:189], v[120:123]
	v_mfma_f32_16x16x32_bf16 v[102:105], v[170:173], v[194:197], v[102:105]
	v_mfma_f32_16x16x32_bf16 v[98:101], v[178:181], v[194:197], v[98:101]
	v_mfma_f32_16x16x32_bf16 v[86:89], v[170:173], v[214:217], v[86:89]
	v_mfma_f32_16x16x32_bf16 v[82:85], v[178:181], v[214:217], v[82:85]
	v_mfma_f32_16x16x32_bf16 v[70:73], v[170:173], v[222:225], v[70:73]
	v_mfma_f32_16x16x32_bf16 v[66:69], v[178:181], v[222:225], v[66:69]
	v_mfma_f32_16x16x32_bf16 v[124:127], v[174:177], v[190:193], v[124:127]
	v_mfma_f32_16x16x32_bf16 v[120:123], v[182:185], v[190:193], v[120:123]
	v_mfma_f32_16x16x32_bf16 v[102:105], v[174:177], v[210:213], v[102:105]
	v_mfma_f32_16x16x32_bf16 v[98:101], v[182:185], v[210:213], v[98:101]
	v_mfma_f32_16x16x32_bf16 v[86:89], v[174:177], v[218:221], v[86:89]
	v_mfma_f32_16x16x32_bf16 v[82:85], v[182:185], v[218:221], v[82:85]
	v_mfma_f32_16x16x32_bf16 v[70:73], v[174:177], v[226:229], v[70:73]
	v_mfma_f32_16x16x32_bf16 v[66:69], v[182:185], v[226:229], v[66:69]
	s_barrier
	s_setprio 1
	s_add_i32 s10, s12, s60
	v_lshl_add_u64 v[166:167], s[50:51], 0, v[144:145]
	s_mov_b32 m0, s10
	ds_read_b128 v[186:189], v169 offset:16384
	ds_read_b128 v[190:193], v169 offset:17408
	ds_read_b128 v[194:197], v169 offset:18432
	ds_read_b128 v[210:213], v169 offset:19456
	ds_read_b128 v[214:217], v169 offset:20480
	ds_read_b128 v[218:221], v169 offset:21504
	ds_read_b128 v[222:225], v169 offset:22528
	ds_read_b128 v[226:229], v169 offset:23552
	global_load_lds_dwordx4 v[166:167], off
	s_add_i32 m0, s10, 0x2000
	s_add_u32 s10, s50, 0x20000
	v_lshl_add_u64 v[198:199], s[50:51], 0, v[148:149]
	s_addc_u32 s11, s51, 0
	s_add_i32 s12, s13, s60
	global_load_lds_dwordx4 v[198:199], off
	v_lshl_add_u64 v[202:203], s[10:11], 0, v[144:145]
	s_mov_b32 m0, s12
	v_lshl_add_u64 v[236:237], s[52:53], 0, v[146:147]
	global_load_lds_dwordx4 v[202:203], off
	v_lshl_add_u64 v[202:203], s[10:11], 0, v[148:149]
	s_add_i32 m0, s12, 0x2000
	s_nop 0
	global_load_lds_dwordx4 v[202:203], off
	v_lshl_add_u64 v[202:203], s[52:53], 0, v[116:117]
	s_mov_b32 m0, s31
	s_nop 0
	global_load_lds_dwordx4 v[202:203], off
	s_mov_b32 m0, s61
	s_nop 0
	global_load_lds_dwordx4 v[236:237], off
	s_waitcnt vmcnt(8)
	s_waitcnt lgkmcnt(0)
	s_setprio 0
	s_barrier
	v_mfma_f32_16x16x32_bf16 v[62:65], v[136:139], v[186:189], v[62:65]
	v_mfma_f32_16x16x32_bf16 v[58:61], v[158:161], v[186:189], v[58:61]
	v_mfma_f32_16x16x32_bf16 v[50:53], v[136:139], v[194:197], v[50:53]
	v_mfma_f32_16x16x32_bf16 v[42:45], v[158:161], v[194:197], v[42:45]
	v_mfma_f32_16x16x32_bf16 v[34:37], v[136:139], v[214:217], v[34:37]
	v_mfma_f32_16x16x32_bf16 v[26:29], v[158:161], v[214:217], v[26:29]
	v_mfma_f32_16x16x32_bf16 v[18:21], v[136:139], v[222:225], v[18:21]
	v_mfma_f32_16x16x32_bf16 v[10:13], v[158:161], v[222:225], v[10:13]
	v_mfma_f32_16x16x32_bf16 v[62:65], v[140:143], v[190:193], v[62:65]
	v_mfma_f32_16x16x32_bf16 v[58:61], v[162:165], v[190:193], v[58:61]
	v_mfma_f32_16x16x32_bf16 v[50:53], v[140:143], v[210:213], v[50:53]
	v_mfma_f32_16x16x32_bf16 v[42:45], v[162:165], v[210:213], v[42:45]
	v_mfma_f32_16x16x32_bf16 v[34:37], v[140:143], v[218:221], v[34:37]
	v_mfma_f32_16x16x32_bf16 v[26:29], v[162:165], v[218:221], v[26:29]
	v_mfma_f32_16x16x32_bf16 v[18:21], v[140:143], v[226:229], v[18:21]
	v_mfma_f32_16x16x32_bf16 v[10:13], v[162:165], v[226:229], v[10:13]
	v_mfma_f32_16x16x32_bf16 v[54:57], v[170:173], v[186:189], v[54:57]
	v_mfma_f32_16x16x32_bf16 v[46:49], v[178:181], v[186:189], v[46:49]
	v_mfma_f32_16x16x32_bf16 v[38:41], v[170:173], v[194:197], v[38:41]
	v_mfma_f32_16x16x32_bf16 v[30:33], v[178:181], v[194:197], v[30:33]
	v_mfma_f32_16x16x32_bf16 v[22:25], v[170:173], v[214:217], v[22:25]
	v_mfma_f32_16x16x32_bf16 v[14:17], v[178:181], v[214:217], v[14:17]
	v_mfma_f32_16x16x32_bf16 v[6:9], v[170:173], v[222:225], v[6:9]
	v_mfma_f32_16x16x32_bf16 v[2:5], v[178:181], v[222:225], v[2:5]
	v_mfma_f32_16x16x32_bf16 v[54:57], v[174:177], v[190:193], v[54:57]
	v_mfma_f32_16x16x32_bf16 v[46:49], v[182:185], v[190:193], v[46:49]
	v_mfma_f32_16x16x32_bf16 v[38:41], v[174:177], v[210:213], v[38:41]
	v_mfma_f32_16x16x32_bf16 v[30:33], v[182:185], v[210:213], v[30:33]
	v_mfma_f32_16x16x32_bf16 v[22:25], v[174:177], v[218:221], v[22:25]
	v_mfma_f32_16x16x32_bf16 v[14:17], v[182:185], v[218:221], v[14:17]
	v_mfma_f32_16x16x32_bf16 v[6:9], v[174:177], v[226:229], v[6:9]
	v_mfma_f32_16x16x32_bf16 v[2:5], v[182:185], v[226:229], v[2:5]
	s_barrier
	s_setprio 1
	s_add_i32 s12, 0, 0x18000
	v_add_u32_e32 v114, s12, v119
	s_add_i32 s13, 0, 0x1c000
	ds_read_b128 v[136:139], v114
	ds_read_b128 v[140:143], v114 offset:1024
	ds_read_b128 v[158:161], v114 offset:2048
	ds_read_b128 v[162:165], v114 offset:3072
	v_add_u32_e32 v114, s13, v119
	ds_read_b128 v[170:173], v114
	ds_read_b128 v[174:177], v114 offset:1024
	ds_read_b128 v[178:181], v114 offset:2048
	ds_read_b128 v[182:185], v114 offset:3072
	s_add_u32 s10, s52, 0x20000
	s_addc_u32 s11, s53, 0
	s_mov_b32 m0, s62
	v_lshl_add_u64 v[238:239], s[10:11], 0, v[116:117]
	ds_read_b128 v[186:189], v169 offset:32768
	ds_read_b128 v[190:193], v169 offset:33792
	ds_read_b128 v[194:197], v169 offset:34816
	ds_read_b128 v[210:213], v169 offset:35840
	ds_read_b128 v[214:217], v169 offset:36864
	ds_read_b128 v[218:221], v169 offset:37888
	ds_read_b128 v[222:225], v169 offset:38912
	ds_read_b128 v[226:229], v169 offset:39936
	global_load_lds_dwordx4 v[238:239], off
	v_lshl_add_u64 v[238:239], s[10:11], 0, v[146:147]
	s_mov_b32 m0, s63
	s_nop 0
	global_load_lds_dwordx4 v[238:239], off
	s_waitcnt vmcnt(8)
	s_waitcnt lgkmcnt(0)
	s_setprio 0
	s_barrier
	v_mfma_f32_16x16x32_bf16 v[132:135], v[136:139], v[186:189], v[132:135]
	v_mfma_f32_16x16x32_bf16 v[128:131], v[158:161], v[186:189], v[128:131]
	v_mfma_f32_16x16x32_bf16 v[110:113], v[136:139], v[194:197], v[110:113]
	v_mfma_f32_16x16x32_bf16 v[106:109], v[158:161], v[194:197], v[106:109]
	v_mfma_f32_16x16x32_bf16 v[94:97], v[136:139], v[214:217], v[94:97]
	v_mfma_f32_16x16x32_bf16 v[90:93], v[158:161], v[214:217], v[90:93]
	v_mfma_f32_16x16x32_bf16 v[78:81], v[136:139], v[222:225], v[78:81]
	v_mfma_f32_16x16x32_bf16 v[74:77], v[158:161], v[222:225], v[74:77]
	v_mfma_f32_16x16x32_bf16 v[132:135], v[140:143], v[190:193], v[132:135]
	v_mfma_f32_16x16x32_bf16 v[128:131], v[162:165], v[190:193], v[128:131]
	v_mfma_f32_16x16x32_bf16 v[110:113], v[140:143], v[210:213], v[110:113]
	v_mfma_f32_16x16x32_bf16 v[106:109], v[162:165], v[210:213], v[106:109]
	v_mfma_f32_16x16x32_bf16 v[94:97], v[140:143], v[218:221], v[94:97]
	v_mfma_f32_16x16x32_bf16 v[90:93], v[162:165], v[218:221], v[90:93]
	v_mfma_f32_16x16x32_bf16 v[78:81], v[140:143], v[226:229], v[78:81]
	v_mfma_f32_16x16x32_bf16 v[74:77], v[162:165], v[226:229], v[74:77]
	v_mfma_f32_16x16x32_bf16 v[124:127], v[170:173], v[186:189], v[124:127]
	v_mfma_f32_16x16x32_bf16 v[120:123], v[178:181], v[186:189], v[120:123]
	v_mfma_f32_16x16x32_bf16 v[102:105], v[170:173], v[194:197], v[102:105]
	v_mfma_f32_16x16x32_bf16 v[98:101], v[178:181], v[194:197], v[98:101]
	v_mfma_f32_16x16x32_bf16 v[86:89], v[170:173], v[214:217], v[86:89]
	v_mfma_f32_16x16x32_bf16 v[82:85], v[178:181], v[214:217], v[82:85]
	v_mfma_f32_16x16x32_bf16 v[70:73], v[170:173], v[222:225], v[70:73]
	v_mfma_f32_16x16x32_bf16 v[66:69], v[178:181], v[222:225], v[66:69]
	v_mfma_f32_16x16x32_bf16 v[124:127], v[174:177], v[190:193], v[124:127]
	v_mfma_f32_16x16x32_bf16 v[120:123], v[182:185], v[190:193], v[120:123]
	v_mfma_f32_16x16x32_bf16 v[102:105], v[174:177], v[210:213], v[102:105]
	v_mfma_f32_16x16x32_bf16 v[98:101], v[182:185], v[210:213], v[98:101]
	v_mfma_f32_16x16x32_bf16 v[86:89], v[174:177], v[218:221], v[86:89]
	v_mfma_f32_16x16x32_bf16 v[82:85], v[182:185], v[218:221], v[82:85]
	v_mfma_f32_16x16x32_bf16 v[70:73], v[174:177], v[226:229], v[70:73]
	v_mfma_f32_16x16x32_bf16 v[66:69], v[182:185], v[226:229], v[66:69]
	s_barrier
	s_setprio 1
	s_add_i32 s10, s12, s60
	v_lshl_add_u64 v[166:167], v[166:167], 0, s[20:21]
	s_mov_b32 m0, s10
	ds_read_b128 v[186:189], v169 offset:49152
	ds_read_b128 v[190:193], v169 offset:50176
	ds_read_b128 v[194:197], v169 offset:51200
	ds_read_b128 v[210:213], v169 offset:52224
	ds_read_b128 v[214:217], v169 offset:53248
	ds_read_b128 v[218:221], v169 offset:54272
	ds_read_b128 v[222:225], v169 offset:55296
	ds_read_b128 v[226:229], v169 offset:56320
	global_load_lds_dwordx4 v[166:167], off
	s_add_i32 m0, s10, 0x2000
	s_add_u32 s10, s50, 0x20080
	v_lshl_add_u64 v[166:167], v[198:199], 0, s[20:21]
	s_addc_u32 s11, s51, 0
	s_add_i32 s12, s13, s60
	global_load_lds_dwordx4 v[166:167], off
	v_lshl_add_u64 v[166:167], s[10:11], 0, v[144:145]
	s_mov_b32 m0, s12
	s_nop 0
	global_load_lds_dwordx4 v[166:167], off
	v_lshl_add_u64 v[166:167], s[10:11], 0, v[148:149]
	s_add_i32 m0, s12, 0x2000
	s_nop 0
	global_load_lds_dwordx4 v[166:167], off
	v_lshl_add_u64 v[166:167], v[202:203], 0, s[20:21]
	s_mov_b32 m0, s64
	s_nop 0
	global_load_lds_dwordx4 v[166:167], off
	v_lshl_add_u64 v[166:167], v[236:237], 0, s[20:21]
	s_mov_b32 m0, s65
	s_nop 0
	global_load_lds_dwordx4 v[166:167], off
	s_waitcnt vmcnt(8)
	s_waitcnt lgkmcnt(0)
	s_setprio 0
	s_barrier
	v_mfma_f32_16x16x32_bf16 v[62:65], v[136:139], v[186:189], v[62:65]
	v_mfma_f32_16x16x32_bf16 v[58:61], v[158:161], v[186:189], v[58:61]
	v_mfma_f32_16x16x32_bf16 v[50:53], v[136:139], v[194:197], v[50:53]
	v_mfma_f32_16x16x32_bf16 v[42:45], v[158:161], v[194:197], v[42:45]
	v_mfma_f32_16x16x32_bf16 v[34:37], v[136:139], v[214:217], v[34:37]
	v_mfma_f32_16x16x32_bf16 v[26:29], v[158:161], v[214:217], v[26:29]
	v_mfma_f32_16x16x32_bf16 v[18:21], v[136:139], v[222:225], v[18:21]
	v_mfma_f32_16x16x32_bf16 v[10:13], v[158:161], v[222:225], v[10:13]
	v_mfma_f32_16x16x32_bf16 v[62:65], v[140:143], v[190:193], v[62:65]
	v_mfma_f32_16x16x32_bf16 v[58:61], v[162:165], v[190:193], v[58:61]
	v_mfma_f32_16x16x32_bf16 v[50:53], v[140:143], v[210:213], v[50:53]
	v_mfma_f32_16x16x32_bf16 v[42:45], v[162:165], v[210:213], v[42:45]
	v_mfma_f32_16x16x32_bf16 v[34:37], v[140:143], v[218:221], v[34:37]
	v_mfma_f32_16x16x32_bf16 v[26:29], v[162:165], v[218:221], v[26:29]
	v_mfma_f32_16x16x32_bf16 v[18:21], v[140:143], v[226:229], v[18:21]
	v_mfma_f32_16x16x32_bf16 v[10:13], v[162:165], v[226:229], v[10:13]
	v_mfma_f32_16x16x32_bf16 v[54:57], v[170:173], v[186:189], v[54:57]
	v_mfma_f32_16x16x32_bf16 v[46:49], v[178:181], v[186:189], v[46:49]
	v_mfma_f32_16x16x32_bf16 v[38:41], v[170:173], v[194:197], v[38:41]
	v_mfma_f32_16x16x32_bf16 v[30:33], v[178:181], v[194:197], v[30:33]
	v_mfma_f32_16x16x32_bf16 v[22:25], v[170:173], v[214:217], v[22:25]
	v_mfma_f32_16x16x32_bf16 v[14:17], v[178:181], v[214:217], v[14:17]
	v_mfma_f32_16x16x32_bf16 v[6:9], v[170:173], v[222:225], v[6:9]
	v_mfma_f32_16x16x32_bf16 v[2:5], v[178:181], v[222:225], v[2:5]
	v_mfma_f32_16x16x32_bf16 v[54:57], v[174:177], v[190:193], v[54:57]
	v_mfma_f32_16x16x32_bf16 v[46:49], v[182:185], v[190:193], v[46:49]
	v_mfma_f32_16x16x32_bf16 v[38:41], v[174:177], v[210:213], v[38:41]
	v_mfma_f32_16x16x32_bf16 v[30:33], v[182:185], v[210:213], v[30:33]
	v_mfma_f32_16x16x32_bf16 v[22:25], v[174:177], v[218:221], v[22:25]
	v_mfma_f32_16x16x32_bf16 v[14:17], v[182:185], v[218:221], v[14:17]
	v_mfma_f32_16x16x32_bf16 v[6:9], v[174:177], v[226:229], v[6:9]
	v_mfma_f32_16x16x32_bf16 v[2:5], v[182:185], v[226:229], v[2:5]
	s_barrier
	s_setprio 1
	s_add_i32 s9, s9, 2
	s_add_u32 s48, s48, 0x100
	s_addc_u32 s49, s49, 0
	s_add_u32 s7, s7, 0x100
	s_addc_u32 s8, s8, 0
	s_cmp_gt_u32 s9, 5
	s_cbranch_scc0 .LBB0_514
	s_setprio 0
	s_and_b64 vcc, exec, s[26:27]
	s_cbranch_vccz .LBB0_517
	s_barrier

.LBB0_883:
	s_add_i32 s10, s11, 2
	s_add_u32 s12, s0, 0xfff00080
	s_addc_u32 s13, s1, -1
	s_add_i32 s14, 0, 0x10000
	s_cmp_eq_u32 s7, s11
	s_cselect_b32 s27, s3, s13
	s_cselect_b32 s26, s4, s12
	v_add_u32_e32 v114, s14, v119
	s_cselect_b32 s25, s5, s9
	s_cselect_b32 s24, s6, s8
	s_add_i32 s11, 0, 0x14000
	s_waitcnt lgkmcnt(0)
	ds_read_b128 v[136:139], v114
	ds_read_b128 v[140:143], v114 offset:1024
	ds_read_b128 v[158:161], v114 offset:2048
	ds_read_b128 v[162:165], v114 offset:3072
	v_add_u32_e32 v114, s11, v119
	ds_read_b128 v[166:169], v114
	ds_read_b128 v[170:173], v114 offset:1024
	ds_read_b128 v[174:177], v114 offset:2048
	ds_read_b128 v[180:183], v114 offset:3072
	v_lshl_add_u64 v[116:117], s[0:1], 0, v[154:155]
	s_add_i32 m0, s47, 0xc000
	ds_read_b128 v[184:187], v179
	ds_read_b128 v[188:191], v179 offset:1024
	ds_read_b128 v[192:195], v179 offset:2048
	ds_read_b128 v[196:199], v179 offset:3072
	ds_read_b128 v[210:213], v179 offset:4096
	ds_read_b128 v[214:217], v179 offset:5120
	ds_read_b128 v[218:221], v179 offset:6144
	ds_read_b128 v[222:225], v179 offset:7168
	global_load_lds_dwordx4 v[116:117], off
	v_lshl_add_u64 v[116:117], s[0:1], 0, v[156:157]
	s_add_i32 m0, s47, 0xe000
	s_nop 0
	global_load_lds_dwordx4 v[116:117], off
	s_waitcnt vmcnt(8)
	s_waitcnt lgkmcnt(0)
	s_setprio 0
	s_barrier
	v_mfma_f32_16x16x32_bf16 v[132:135], v[136:139], v[184:187], v[132:135]
	v_mfma_f32_16x16x32_bf16 v[128:131], v[158:161], v[184:187], v[128:131]
	v_mfma_f32_16x16x32_bf16 v[124:127], v[136:139], v[192:195], v[124:127]
	v_mfma_f32_16x16x32_bf16 v[120:123], v[158:161], v[192:195], v[120:123]
	v_mfma_f32_16x16x32_bf16 v[110:113], v[136:139], v[210:213], v[110:113]
	v_mfma_f32_16x16x32_bf16 v[106:109], v[158:161], v[210:213], v[106:109]
	v_mfma_f32_16x16x32_bf16 v[102:105], v[136:139], v[218:221], v[102:105]
	v_mfma_f32_16x16x32_bf16 v[98:101], v[158:161], v[218:221], v[98:101]
	v_mfma_f32_16x16x32_bf16 v[132:135], v[140:143], v[188:191], v[132:135]
	v_mfma_f32_16x16x32_bf16 v[128:131], v[162:165], v[188:191], v[128:131]
	v_mfma_f32_16x16x32_bf16 v[124:127], v[140:143], v[196:199], v[124:127]
	v_mfma_f32_16x16x32_bf16 v[120:123], v[162:165], v[196:199], v[120:123]
	v_mfma_f32_16x16x32_bf16 v[110:113], v[140:143], v[214:217], v[110:113]
	v_mfma_f32_16x16x32_bf16 v[106:109], v[162:165], v[214:217], v[106:109]
	v_mfma_f32_16x16x32_bf16 v[102:105], v[140:143], v[222:225], v[102:105]
	v_mfma_f32_16x16x32_bf16 v[98:101], v[162:165], v[222:225], v[98:101]
	v_mfma_f32_16x16x32_bf16 v[94:97], v[166:169], v[184:187], v[94:97]
	v_mfma_f32_16x16x32_bf16 v[90:93], v[174:177], v[184:187], v[90:93]
	v_mfma_f32_16x16x32_bf16 v[86:89], v[166:169], v[192:195], v[86:89]
	v_mfma_f32_16x16x32_bf16 v[82:85], v[174:177], v[192:195], v[82:85]
	v_mfma_f32_16x16x32_bf16 v[78:81], v[166:169], v[210:213], v[78:81]
	v_mfma_f32_16x16x32_bf16 v[74:77], v[174:177], v[210:213], v[74:77]
	v_mfma_f32_16x16x32_bf16 v[70:73], v[166:169], v[218:221], v[70:73]
	v_mfma_f32_16x16x32_bf16 v[66:69], v[174:177], v[218:221], v[66:69]
	v_mfma_f32_16x16x32_bf16 v[94:97], v[170:173], v[188:191], v[94:97]
	v_mfma_f32_16x16x32_bf16 v[90:93], v[180:183], v[188:191], v[90:93]
	v_mfma_f32_16x16x32_bf16 v[86:89], v[170:173], v[196:199], v[86:89]
	v_mfma_f32_16x16x32_bf16 v[82:85], v[180:183], v[196:199], v[82:85]
	v_mfma_f32_16x16x32_bf16 v[78:81], v[170:173], v[214:217], v[78:81]
	v_mfma_f32_16x16x32_bf16 v[74:77], v[180:183], v[214:217], v[74:77]
	v_mfma_f32_16x16x32_bf16 v[70:73], v[170:173], v[222:225], v[70:73]
	v_mfma_f32_16x16x32_bf16 v[66:69], v[180:183], v[222:225], v[66:69]
	s_barrier
	s_setprio 1
	s_add_i32 s12, s14, s75
	v_lshl_add_u64 v[116:117], s[24:25], 0, v[146:147]
	s_mov_b32 m0, s12
	ds_read_b128 v[184:187], v179 offset:16384
	ds_read_b128 v[188:191], v179 offset:17408
	ds_read_b128 v[192:195], v179 offset:18432
	ds_read_b128 v[196:199], v179 offset:19456
	ds_read_b128 v[210:213], v179 offset:20480
	ds_read_b128 v[214:217], v179 offset:21504
	ds_read_b128 v[218:221], v179 offset:22528
	ds_read_b128 v[222:225], v179 offset:23552
	global_load_lds_dwordx4 v[116:117], off
	s_add_i32 m0, s12, 0x2000
	s_add_u32 s12, s24, 0x100000
	v_lshl_add_u64 v[202:203], s[24:25], 0, v[150:151]
	s_addc_u32 s13, s25, 0
	s_add_i32 s11, s11, s75
	global_load_lds_dwordx4 v[202:203], off
	v_lshl_add_u64 v[226:227], s[12:13], 0, v[146:147]
	s_mov_b32 m0, s11
	v_lshl_add_u64 v[228:229], s[26:27], 0, v[148:149]
	global_load_lds_dwordx4 v[226:227], off
	v_lshl_add_u64 v[226:227], s[12:13], 0, v[150:151]
	s_add_i32 m0, s11, 0x2000
	s_nop 0
	global_load_lds_dwordx4 v[226:227], off
	v_lshl_add_u64 v[226:227], s[26:27], 0, v[144:145]
	s_mov_b32 m0, s47
	s_nop 0
	global_load_lds_dwordx4 v[226:227], off
	s_mov_b32 m0, s80
	s_nop 0
	global_load_lds_dwordx4 v[228:229], off
	s_waitcnt vmcnt(8)
	s_waitcnt lgkmcnt(0)
	s_setprio 0
	s_barrier
	v_mfma_f32_16x16x32_bf16 v[62:65], v[136:139], v[184:187], v[62:65]
	v_mfma_f32_16x16x32_bf16 v[58:61], v[158:161], v[184:187], v[58:61]
	v_mfma_f32_16x16x32_bf16 v[54:57], v[136:139], v[192:195], v[54:57]
	v_mfma_f32_16x16x32_bf16 v[50:53], v[158:161], v[192:195], v[50:53]
	v_mfma_f32_16x16x32_bf16 v[46:49], v[136:139], v[210:213], v[46:49]
	v_mfma_f32_16x16x32_bf16 v[42:45], v[158:161], v[210:213], v[42:45]
	v_mfma_f32_16x16x32_bf16 v[38:41], v[136:139], v[218:221], v[38:41]
	v_mfma_f32_16x16x32_bf16 v[34:37], v[158:161], v[218:221], v[34:37]
	v_mfma_f32_16x16x32_bf16 v[62:65], v[140:143], v[188:191], v[62:65]
	v_mfma_f32_16x16x32_bf16 v[58:61], v[162:165], v[188:191], v[58:61]
	v_mfma_f32_16x16x32_bf16 v[54:57], v[140:143], v[196:199], v[54:57]
	v_mfma_f32_16x16x32_bf16 v[50:53], v[162:165], v[196:199], v[50:53]
	v_mfma_f32_16x16x32_bf16 v[46:49], v[140:143], v[214:217], v[46:49]
	v_mfma_f32_16x16x32_bf16 v[42:45], v[162:165], v[214:217], v[42:45]
	v_mfma_f32_16x16x32_bf16 v[38:41], v[140:143], v[222:225], v[38:41]
	v_mfma_f32_16x16x32_bf16 v[34:37], v[162:165], v[222:225], v[34:37]
	v_mfma_f32_16x16x32_bf16 v[30:33], v[166:169], v[184:187], v[30:33]
	v_mfma_f32_16x16x32_bf16 v[26:29], v[174:177], v[184:187], v[26:29]
	v_mfma_f32_16x16x32_bf16 v[22:25], v[166:169], v[192:195], v[22:25]
	v_mfma_f32_16x16x32_bf16 v[18:21], v[174:177], v[192:195], v[18:21]
	v_mfma_f32_16x16x32_bf16 v[14:17], v[166:169], v[210:213], v[14:17]
	v_mfma_f32_16x16x32_bf16 v[10:13], v[174:177], v[210:213], v[10:13]
	v_mfma_f32_16x16x32_bf16 v[6:9], v[166:169], v[218:221], v[6:9]
	v_mfma_f32_16x16x32_bf16 v[2:5], v[174:177], v[218:221], v[2:5]
	v_mfma_f32_16x16x32_bf16 v[30:33], v[170:173], v[188:191], v[30:33]
	v_mfma_f32_16x16x32_bf16 v[26:29], v[180:183], v[188:191], v[26:29]
	v_mfma_f32_16x16x32_bf16 v[22:25], v[170:173], v[196:199], v[22:25]
	v_mfma_f32_16x16x32_bf16 v[18:21], v[180:183], v[196:199], v[18:21]
	v_mfma_f32_16x16x32_bf16 v[14:17], v[170:173], v[214:217], v[14:17]
	v_mfma_f32_16x16x32_bf16 v[10:13], v[180:183], v[214:217], v[10:13]
	v_mfma_f32_16x16x32_bf16 v[6:9], v[170:173], v[222:225], v[6:9]
	v_mfma_f32_16x16x32_bf16 v[2:5], v[180:183], v[222:225], v[2:5]
	s_barrier
	s_setprio 1
	s_add_i32 s11, 0, 0x18000
	v_add_u32_e32 v114, s11, v119
	s_add_i32 s14, 0, 0x1c000
	ds_read_b128 v[136:139], v114
	ds_read_b128 v[140:143], v114 offset:1024
	ds_read_b128 v[158:161], v114 offset:2048
	ds_read_b128 v[162:165], v114 offset:3072
	v_add_u32_e32 v114, s14, v119
	ds_read_b128 v[166:169], v114
	ds_read_b128 v[170:173], v114 offset:1024
	ds_read_b128 v[174:177], v114 offset:2048
	ds_read_b128 v[180:183], v114 offset:3072
	s_add_u32 s12, s26, 0x100000
	s_addc_u32 s13, s27, 0
	s_mov_b32 m0, s81
	v_lshl_add_u64 v[236:237], s[12:13], 0, v[144:145]
	ds_read_b128 v[184:187], v179 offset:32768
	ds_read_b128 v[188:191], v179 offset:33792
	ds_read_b128 v[192:195], v179 offset:34816
	ds_read_b128 v[196:199], v179 offset:35840
	ds_read_b128 v[210:213], v179 offset:36864
	ds_read_b128 v[214:217], v179 offset:37888
	ds_read_b128 v[218:221], v179 offset:38912
	ds_read_b128 v[222:225], v179 offset:39936
	global_load_lds_dwordx4 v[236:237], off
	v_lshl_add_u64 v[236:237], s[12:13], 0, v[148:149]
	s_mov_b32 m0, s82
	s_nop 0
	global_load_lds_dwordx4 v[236:237], off
	s_waitcnt vmcnt(8)
	s_waitcnt lgkmcnt(0)
	s_setprio 0
	s_barrier
	v_mfma_f32_16x16x32_bf16 v[132:135], v[136:139], v[184:187], v[132:135]
	v_mfma_f32_16x16x32_bf16 v[128:131], v[158:161], v[184:187], v[128:131]
	v_mfma_f32_16x16x32_bf16 v[124:127], v[136:139], v[192:195], v[124:127]
	v_mfma_f32_16x16x32_bf16 v[120:123], v[158:161], v[192:195], v[120:123]
	v_mfma_f32_16x16x32_bf16 v[110:113], v[136:139], v[210:213], v[110:113]
	v_mfma_f32_16x16x32_bf16 v[106:109], v[158:161], v[210:213], v[106:109]
	v_mfma_f32_16x16x32_bf16 v[102:105], v[136:139], v[218:221], v[102:105]
	v_mfma_f32_16x16x32_bf16 v[98:101], v[158:161], v[218:221], v[98:101]
	v_mfma_f32_16x16x32_bf16 v[132:135], v[140:143], v[188:191], v[132:135]
	v_mfma_f32_16x16x32_bf16 v[128:131], v[162:165], v[188:191], v[128:131]
	v_mfma_f32_16x16x32_bf16 v[124:127], v[140:143], v[196:199], v[124:127]
	v_mfma_f32_16x16x32_bf16 v[120:123], v[162:165], v[196:199], v[120:123]
	v_mfma_f32_16x16x32_bf16 v[110:113], v[140:143], v[214:217], v[110:113]
	v_mfma_f32_16x16x32_bf16 v[106:109], v[162:165], v[214:217], v[106:109]
	v_mfma_f32_16x16x32_bf16 v[102:105], v[140:143], v[222:225], v[102:105]
	v_mfma_f32_16x16x32_bf16 v[98:101], v[162:165], v[222:225], v[98:101]
	v_mfma_f32_16x16x32_bf16 v[94:97], v[166:169], v[184:187], v[94:97]
	v_mfma_f32_16x16x32_bf16 v[90:93], v[174:177], v[184:187], v[90:93]
	v_mfma_f32_16x16x32_bf16 v[86:89], v[166:169], v[192:195], v[86:89]
	v_mfma_f32_16x16x32_bf16 v[82:85], v[174:177], v[192:195], v[82:85]
	v_mfma_f32_16x16x32_bf16 v[78:81], v[166:169], v[210:213], v[78:81]
	v_mfma_f32_16x16x32_bf16 v[74:77], v[174:177], v[210:213], v[74:77]
	v_mfma_f32_16x16x32_bf16 v[70:73], v[166:169], v[218:221], v[70:73]
	v_mfma_f32_16x16x32_bf16 v[66:69], v[174:177], v[218:221], v[66:69]
	v_mfma_f32_16x16x32_bf16 v[94:97], v[170:173], v[188:191], v[94:97]
	v_mfma_f32_16x16x32_bf16 v[90:93], v[180:183], v[188:191], v[90:93]
	v_mfma_f32_16x16x32_bf16 v[86:89], v[170:173], v[196:199], v[86:89]
	v_mfma_f32_16x16x32_bf16 v[82:85], v[180:183], v[196:199], v[82:85]
	v_mfma_f32_16x16x32_bf16 v[78:81], v[170:173], v[214:217], v[78:81]
	v_mfma_f32_16x16x32_bf16 v[74:77], v[180:183], v[214:217], v[74:77]
	v_mfma_f32_16x16x32_bf16 v[70:73], v[170:173], v[222:225], v[70:73]
	v_mfma_f32_16x16x32_bf16 v[66:69], v[180:183], v[222:225], v[66:69]
	s_barrier
	s_setprio 1
	s_add_i32 s11, s11, s75
	v_lshl_add_u64 v[116:117], v[116:117], 0, s[20:21]
	s_mov_b32 m0, s11
	ds_read_b128 v[184:187], v179 offset:49152
	ds_read_b128 v[188:191], v179 offset:50176
	ds_read_b128 v[192:195], v179 offset:51200
	ds_read_b128 v[196:199], v179 offset:52224
	ds_read_b128 v[210:213], v179 offset:53248
	ds_read_b128 v[214:217], v179 offset:54272
	ds_read_b128 v[218:221], v179 offset:55296
	ds_read_b128 v[222:225], v179 offset:56320
	global_load_lds_dwordx4 v[116:117], off
	s_add_i32 m0, s11, 0x2000
	s_add_u32 s12, s24, 0x100080
	v_lshl_add_u64 v[116:117], v[202:203], 0, s[20:21]
	s_addc_u32 s13, s25, 0
	s_add_i32 s11, s14, s75
	global_load_lds_dwordx4 v[116:117], off
	v_lshl_add_u64 v[116:117], s[12:13], 0, v[146:147]
	s_mov_b32 m0, s11
	s_nop 0
	global_load_lds_dwordx4 v[116:117], off
	v_lshl_add_u64 v[116:117], s[12:13], 0, v[150:151]
	s_add_i32 m0, s11, 0x2000
	s_nop 0
	global_load_lds_dwordx4 v[116:117], off
	v_lshl_add_u64 v[116:117], v[226:227], 0, s[20:21]
	s_mov_b32 m0, s83
	s_nop 0
	global_load_lds_dwordx4 v[116:117], off
	v_lshl_add_u64 v[116:117], v[228:229], 0, s[20:21]
	s_mov_b32 m0, s84
	s_nop 0
	global_load_lds_dwordx4 v[116:117], off
	s_waitcnt vmcnt(8)
	s_waitcnt lgkmcnt(0)
	s_setprio 0
	s_barrier
	v_mfma_f32_16x16x32_bf16 v[62:65], v[136:139], v[184:187], v[62:65]
	v_mfma_f32_16x16x32_bf16 v[58:61], v[158:161], v[184:187], v[58:61]
	v_mfma_f32_16x16x32_bf16 v[54:57], v[136:139], v[192:195], v[54:57]
	v_mfma_f32_16x16x32_bf16 v[50:53], v[158:161], v[192:195], v[50:53]
	v_mfma_f32_16x16x32_bf16 v[46:49], v[136:139], v[210:213], v[46:49]
	v_mfma_f32_16x16x32_bf16 v[42:45], v[158:161], v[210:213], v[42:45]
	v_mfma_f32_16x16x32_bf16 v[38:41], v[136:139], v[218:221], v[38:41]
	v_mfma_f32_16x16x32_bf16 v[34:37], v[158:161], v[218:221], v[34:37]
	v_mfma_f32_16x16x32_bf16 v[62:65], v[140:143], v[188:191], v[62:65]
	v_mfma_f32_16x16x32_bf16 v[58:61], v[162:165], v[188:191], v[58:61]
	v_mfma_f32_16x16x32_bf16 v[54:57], v[140:143], v[196:199], v[54:57]
	v_mfma_f32_16x16x32_bf16 v[50:53], v[162:165], v[196:199], v[50:53]
	v_mfma_f32_16x16x32_bf16 v[46:49], v[140:143], v[214:217], v[46:49]
	v_mfma_f32_16x16x32_bf16 v[42:45], v[162:165], v[214:217], v[42:45]
	v_mfma_f32_16x16x32_bf16 v[38:41], v[140:143], v[222:225], v[38:41]
	v_mfma_f32_16x16x32_bf16 v[34:37], v[162:165], v[222:225], v[34:37]
	v_mfma_f32_16x16x32_bf16 v[30:33], v[166:169], v[184:187], v[30:33]
	v_mfma_f32_16x16x32_bf16 v[26:29], v[174:177], v[184:187], v[26:29]
	v_mfma_f32_16x16x32_bf16 v[22:25], v[166:169], v[192:195], v[22:25]
	v_mfma_f32_16x16x32_bf16 v[18:21], v[174:177], v[192:195], v[18:21]
	v_mfma_f32_16x16x32_bf16 v[14:17], v[166:169], v[210:213], v[14:17]
	v_mfma_f32_16x16x32_bf16 v[10:13], v[174:177], v[210:213], v[10:13]
	v_mfma_f32_16x16x32_bf16 v[6:9], v[166:169], v[218:221], v[6:9]
	v_mfma_f32_16x16x32_bf16 v[2:5], v[174:177], v[218:221], v[2:5]
	v_mfma_f32_16x16x32_bf16 v[30:33], v[170:173], v[188:191], v[30:33]
	v_mfma_f32_16x16x32_bf16 v[26:29], v[180:183], v[188:191], v[26:29]
	v_mfma_f32_16x16x32_bf16 v[22:25], v[170:173], v[196:199], v[22:25]
	v_mfma_f32_16x16x32_bf16 v[18:21], v[180:183], v[196:199], v[18:21]
	v_mfma_f32_16x16x32_bf16 v[14:17], v[170:173], v[214:217], v[14:17]
	v_mfma_f32_16x16x32_bf16 v[10:13], v[180:183], v[214:217], v[10:13]
	v_mfma_f32_16x16x32_bf16 v[6:9], v[170:173], v[222:225], v[6:9]
	v_mfma_f32_16x16x32_bf16 v[2:5], v[180:183], v[222:225], v[2:5]
	s_barrier
	s_setprio 1
	s_add_u32 s0, s0, 0x100
	s_addc_u32 s1, s1, 0
	s_add_u32 s8, s8, 0x100
	s_addc_u32 s9, s9, 0
	s_cmp_ge_i32 s10, s89
	s_mov_b32 s11, s10
	s_cbranch_scc0 .LBB0_883
	s_setprio 0

.LBB0_1165:
	s_mov_b32 s40, s5
	s_ashr_i32 s41, s5, 31
	s_mov_b32 s38, s4
	s_lshl_b64 s[4:5], s[40:41], 21
	s_add_u32 s42, s62, s4
	s_addc_u32 s43, s63, s5
	s_and_b64 s[4:5], s[44:45], exec
	s_cselect_b32 s1, s43, s51
	s_cselect_b32 s4, s42, s50
	s_ashr_i32 s39, s38, 31
	s_lshl_b64 s[6:7], s[38:39], 21
	s_add_u32 s46, s56, s6
	s_addc_u32 s47, s57, s7
	s_and_b64 s[6:7], s[44:45], exec
	s_cselect_b32 s5, s47, s53
	s_cselect_b32 s6, s46, s52
	s_add_u32 s50, s50, 0x100080
	s_addc_u32 s51, s51, 0
	s_add_u32 s7, s52, 0x100
	v_mov_b32_e32 v2, 0
	s_addc_u32 s8, s53, 0
	s_mov_b32 s9, -2
	v_mov_b32_e32 v3, v2
	v_mov_b32_e32 v4, v2
	v_mov_b32_e32 v5, v2
	v_mov_b32_e32 v6, v2
	v_mov_b32_e32 v7, v2
	v_mov_b32_e32 v8, v2
	v_mov_b32_e32 v9, v2
	v_mov_b32_e32 v18, v2
	v_mov_b32_e32 v19, v2
	v_mov_b32_e32 v20, v2
	v_mov_b32_e32 v21, v2
	v_mov_b32_e32 v22, v2
	v_mov_b32_e32 v23, v2
	v_mov_b32_e32 v24, v2
	v_mov_b32_e32 v25, v2
	v_mov_b32_e32 v34, v2
	v_mov_b32_e32 v35, v2
	v_mov_b32_e32 v36, v2
	v_mov_b32_e32 v37, v2
	v_mov_b32_e32 v38, v2
	v_mov_b32_e32 v39, v2
	v_mov_b32_e32 v40, v2
	v_mov_b32_e32 v41, v2
	v_mov_b32_e32 v50, v2
	v_mov_b32_e32 v51, v2
	v_mov_b32_e32 v52, v2
	v_mov_b32_e32 v53, v2
	v_mov_b32_e32 v54, v2
	v_mov_b32_e32 v55, v2
	v_mov_b32_e32 v56, v2
	v_mov_b32_e32 v57, v2
	v_mov_b32_e32 v10, v2
	v_mov_b32_e32 v11, v2
	v_mov_b32_e32 v12, v2
	v_mov_b32_e32 v13, v2
	v_mov_b32_e32 v14, v2
	v_mov_b32_e32 v15, v2
	v_mov_b32_e32 v16, v2
	v_mov_b32_e32 v17, v2
	v_mov_b32_e32 v26, v2
	v_mov_b32_e32 v27, v2
	v_mov_b32_e32 v28, v2
	v_mov_b32_e32 v29, v2
	v_mov_b32_e32 v30, v2
	v_mov_b32_e32 v31, v2
	v_mov_b32_e32 v32, v2
	v_mov_b32_e32 v33, v2
	v_mov_b32_e32 v42, v2
	v_mov_b32_e32 v43, v2
	v_mov_b32_e32 v44, v2
	v_mov_b32_e32 v45, v2
	v_mov_b32_e32 v46, v2
	v_mov_b32_e32 v47, v2
	v_mov_b32_e32 v48, v2
	v_mov_b32_e32 v49, v2
	v_mov_b32_e32 v58, v2
	v_mov_b32_e32 v59, v2
	v_mov_b32_e32 v60, v2
	v_mov_b32_e32 v61, v2
	v_mov_b32_e32 v62, v2
	v_mov_b32_e32 v63, v2
	v_mov_b32_e32 v64, v2
	v_mov_b32_e32 v65, v2
	v_mov_b32_e32 v66, v2
	v_mov_b32_e32 v67, v2
	v_mov_b32_e32 v68, v2
	v_mov_b32_e32 v69, v2
	v_mov_b32_e32 v70, v2
	v_mov_b32_e32 v71, v2
	v_mov_b32_e32 v72, v2
	v_mov_b32_e32 v73, v2
	v_mov_b32_e32 v82, v2
	v_mov_b32_e32 v83, v2
	v_mov_b32_e32 v84, v2
	v_mov_b32_e32 v85, v2
	v_mov_b32_e32 v86, v2
	v_mov_b32_e32 v87, v2
	v_mov_b32_e32 v88, v2
	v_mov_b32_e32 v89, v2
	v_mov_b32_e32 v98, v2
	v_mov_b32_e32 v99, v2
	v_mov_b32_e32 v100, v2
	v_mov_b32_e32 v101, v2
	v_mov_b32_e32 v102, v2
	v_mov_b32_e32 v103, v2
	v_mov_b32_e32 v104, v2
	v_mov_b32_e32 v105, v2
	v_mov_b32_e32 v120, v2
	v_mov_b32_e32 v121, v2
	v_mov_b32_e32 v122, v2
	v_mov_b32_e32 v123, v2
	v_mov_b32_e32 v124, v2
	v_mov_b32_e32 v125, v2
	v_mov_b32_e32 v126, v2
	v_mov_b32_e32 v127, v2
	v_mov_b32_e32 v74, v2
	v_mov_b32_e32 v75, v2
	v_mov_b32_e32 v76, v2
	v_mov_b32_e32 v77, v2
	v_mov_b32_e32 v78, v2
	v_mov_b32_e32 v79, v2
	v_mov_b32_e32 v80, v2
	v_mov_b32_e32 v81, v2
	v_mov_b32_e32 v90, v2
	v_mov_b32_e32 v91, v2
	v_mov_b32_e32 v92, v2
	v_mov_b32_e32 v93, v2
	v_mov_b32_e32 v94, v2
	v_mov_b32_e32 v95, v2
	v_mov_b32_e32 v96, v2
	v_mov_b32_e32 v97, v2
	v_mov_b32_e32 v106, v2
	v_mov_b32_e32 v107, v2
	v_mov_b32_e32 v108, v2
	v_mov_b32_e32 v109, v2
	v_mov_b32_e32 v110, v2
	v_mov_b32_e32 v111, v2
	v_mov_b32_e32 v112, v2
	v_mov_b32_e32 v113, v2
	v_mov_b32_e32 v128, v2
	v_mov_b32_e32 v129, v2
	v_mov_b32_e32 v130, v2
	v_mov_b32_e32 v131, v2
	v_mov_b32_e32 v132, v2
	v_mov_b32_e32 v133, v2
	v_mov_b32_e32 v134, v2
	v_mov_b32_e32 v135, v2
	v_add_u32_e32 v156, 0x10000, v158
.LBB0_1166:
	s_add_u32 s10, s50, 0xfff00080
	s_addc_u32 s11, s51, -1
	s_add_i32 s12, 0, 0x10000
	s_cmp_eq_u32 s9, 60
	s_cselect_b32 s55, s1, s11
	s_cselect_b32 s54, s4, s10
	s_cselect_b32 s53, s5, s8
	s_cselect_b32 s52, s6, s7
	s_add_i32 s13, 0, 0x14000
	ds_read_b128 v[160:163], v156
	ds_read_b128 v[164:167], v156 offset:1024
	ds_read_b128 v[168:171], v156 offset:2048
	ds_read_b128 v[172:175], v156 offset:3072
	ds_read_b128 v[176:179], v156 offset:16384
	ds_read_b128 v[180:183], v156 offset:17408
	ds_read_b128 v[184:187], v156 offset:18432
	ds_read_b128 v[188:191], v156 offset:19456
	s_add_i32 m0, s65, 0xc000
	ds_read_b128 v[192:195], v159
	ds_read_b128 v[196:199], v159 offset:1024
	ds_read_b128 v[210:213], v159 offset:2048
	ds_read_b128 v[214:217], v159 offset:3072
	ds_read_b128 v[218:221], v159 offset:4096
	ds_read_b128 v[222:225], v159 offset:5120
	ds_read_b128 v[226:229], v159 offset:6144
	ds_read_b128 v[236:239], v159 offset:7168
	global_load_lds_dwordx4 v152, s[50:51]
	s_add_i32 m0, s65, 0xe000
	s_nop 0
	global_load_lds_dwordx4 v154, s[50:51]
	s_waitcnt vmcnt(8)
	s_waitcnt lgkmcnt(0)
	s_setprio 0
	s_barrier
	v_mfma_f32_16x16x32_bf16 v[132:135], v[160:163], v[192:195], v[132:135]
	v_mfma_f32_16x16x32_bf16 v[128:131], v[168:171], v[192:195], v[128:131]
	v_mfma_f32_16x16x32_bf16 v[110:113], v[160:163], v[210:213], v[110:113]
	v_mfma_f32_16x16x32_bf16 v[106:109], v[168:171], v[210:213], v[106:109]
	v_mfma_f32_16x16x32_bf16 v[94:97], v[160:163], v[218:221], v[94:97]
	v_mfma_f32_16x16x32_bf16 v[90:93], v[168:171], v[218:221], v[90:93]
	v_mfma_f32_16x16x32_bf16 v[78:81], v[160:163], v[226:229], v[78:81]
	v_mfma_f32_16x16x32_bf16 v[74:77], v[168:171], v[226:229], v[74:77]
	v_mfma_f32_16x16x32_bf16 v[132:135], v[164:167], v[196:199], v[132:135]
	v_mfma_f32_16x16x32_bf16 v[128:131], v[172:175], v[196:199], v[128:131]
	v_mfma_f32_16x16x32_bf16 v[110:113], v[164:167], v[214:217], v[110:113]
	v_mfma_f32_16x16x32_bf16 v[106:109], v[172:175], v[214:217], v[106:109]
	v_mfma_f32_16x16x32_bf16 v[94:97], v[164:167], v[222:225], v[94:97]
	v_mfma_f32_16x16x32_bf16 v[90:93], v[172:175], v[222:225], v[90:93]
	v_mfma_f32_16x16x32_bf16 v[78:81], v[164:167], v[236:239], v[78:81]
	v_mfma_f32_16x16x32_bf16 v[74:77], v[172:175], v[236:239], v[74:77]
	v_mfma_f32_16x16x32_bf16 v[124:127], v[176:179], v[192:195], v[124:127]
	v_mfma_f32_16x16x32_bf16 v[120:123], v[184:187], v[192:195], v[120:123]
	v_mfma_f32_16x16x32_bf16 v[102:105], v[176:179], v[210:213], v[102:105]
	v_mfma_f32_16x16x32_bf16 v[98:101], v[184:187], v[210:213], v[98:101]
	v_mfma_f32_16x16x32_bf16 v[86:89], v[176:179], v[218:221], v[86:89]
	v_mfma_f32_16x16x32_bf16 v[82:85], v[184:187], v[218:221], v[82:85]
	v_mfma_f32_16x16x32_bf16 v[70:73], v[176:179], v[226:229], v[70:73]
	v_mfma_f32_16x16x32_bf16 v[66:69], v[184:187], v[226:229], v[66:69]
	v_mfma_f32_16x16x32_bf16 v[124:127], v[180:183], v[196:199], v[124:127]
	v_mfma_f32_16x16x32_bf16 v[120:123], v[188:191], v[196:199], v[120:123]
	v_mfma_f32_16x16x32_bf16 v[102:105], v[180:183], v[214:217], v[102:105]
	v_mfma_f32_16x16x32_bf16 v[98:101], v[188:191], v[214:217], v[98:101]
	v_mfma_f32_16x16x32_bf16 v[86:89], v[180:183], v[222:225], v[86:89]
	v_mfma_f32_16x16x32_bf16 v[82:85], v[188:191], v[222:225], v[82:85]
	v_mfma_f32_16x16x32_bf16 v[70:73], v[180:183], v[236:239], v[70:73]
	v_mfma_f32_16x16x32_bf16 v[66:69], v[188:191], v[236:239], v[66:69]
	s_barrier
	s_setprio 1
	s_add_i32 s10, s12, s64
	s_mov_b32 m0, s10
	ds_read_b128 v[192:195], v159 offset:16384
	ds_read_b128 v[196:199], v159 offset:17408
	ds_read_b128 v[210:213], v159 offset:18432
	ds_read_b128 v[214:217], v159 offset:19456
	ds_read_b128 v[218:221], v159 offset:20480
	ds_read_b128 v[222:225], v159 offset:21504
	ds_read_b128 v[226:229], v159 offset:22528
	ds_read_b128 v[236:239], v159 offset:23552
	global_load_lds_dwordx4 v136, s[52:53]
	s_add_i32 m0, s10, 0x2000
	s_add_u32 s10, s52, 0x100000
	s_addc_u32 s11, s53, 0
	s_add_i32 s12, s13, s64
	global_load_lds_dwordx4 v140, s[52:53]
	s_mov_b32 m0, s12
	s_nop 0
	global_load_lds_dwordx4 v136, s[10:11]
	s_add_i32 m0, s12, 0x2000
	s_nop 0
	global_load_lds_dwordx4 v140, s[10:11]
	s_mov_b32 m0, s65
	s_nop 0
	global_load_lds_dwordx4 v116, s[54:55]
	s_mov_b32 m0, s66
	s_nop 0
	global_load_lds_dwordx4 v138, s[54:55]
	s_waitcnt vmcnt(8)
	s_waitcnt lgkmcnt(0)
	s_setprio 0
	s_barrier
	v_mfma_f32_16x16x32_bf16 v[62:65], v[160:163], v[192:195], v[62:65]
	v_mfma_f32_16x16x32_bf16 v[58:61], v[168:171], v[192:195], v[58:61]
	v_mfma_f32_16x16x32_bf16 v[46:49], v[160:163], v[210:213], v[46:49]
	v_mfma_f32_16x16x32_bf16 v[42:45], v[168:171], v[210:213], v[42:45]
	v_mfma_f32_16x16x32_bf16 v[30:33], v[160:163], v[218:221], v[30:33]
	v_mfma_f32_16x16x32_bf16 v[26:29], v[168:171], v[218:221], v[26:29]
	v_mfma_f32_16x16x32_bf16 v[14:17], v[160:163], v[226:229], v[14:17]
	v_mfma_f32_16x16x32_bf16 v[10:13], v[168:171], v[226:229], v[10:13]
	v_mfma_f32_16x16x32_bf16 v[62:65], v[164:167], v[196:199], v[62:65]
	v_mfma_f32_16x16x32_bf16 v[58:61], v[172:175], v[196:199], v[58:61]
	v_mfma_f32_16x16x32_bf16 v[46:49], v[164:167], v[214:217], v[46:49]
	v_mfma_f32_16x16x32_bf16 v[42:45], v[172:175], v[214:217], v[42:45]
	v_mfma_f32_16x16x32_bf16 v[30:33], v[164:167], v[222:225], v[30:33]
	v_mfma_f32_16x16x32_bf16 v[26:29], v[172:175], v[222:225], v[26:29]
	v_mfma_f32_16x16x32_bf16 v[14:17], v[164:167], v[236:239], v[14:17]
	v_mfma_f32_16x16x32_bf16 v[10:13], v[172:175], v[236:239], v[10:13]
	v_mfma_f32_16x16x32_bf16 v[54:57], v[176:179], v[192:195], v[54:57]
	v_mfma_f32_16x16x32_bf16 v[50:53], v[184:187], v[192:195], v[50:53]
	v_mfma_f32_16x16x32_bf16 v[38:41], v[176:179], v[210:213], v[38:41]
	v_mfma_f32_16x16x32_bf16 v[34:37], v[184:187], v[210:213], v[34:37]
	v_mfma_f32_16x16x32_bf16 v[22:25], v[176:179], v[218:221], v[22:25]
	v_mfma_f32_16x16x32_bf16 v[18:21], v[184:187], v[218:221], v[18:21]
	v_mfma_f32_16x16x32_bf16 v[6:9], v[176:179], v[226:229], v[6:9]
	v_mfma_f32_16x16x32_bf16 v[2:5], v[184:187], v[226:229], v[2:5]
	v_mfma_f32_16x16x32_bf16 v[54:57], v[180:183], v[196:199], v[54:57]
	v_mfma_f32_16x16x32_bf16 v[50:53], v[188:191], v[196:199], v[50:53]
	v_mfma_f32_16x16x32_bf16 v[38:41], v[180:183], v[214:217], v[38:41]
	v_mfma_f32_16x16x32_bf16 v[34:37], v[188:191], v[214:217], v[34:37]
	v_mfma_f32_16x16x32_bf16 v[22:25], v[180:183], v[222:225], v[22:25]
	v_mfma_f32_16x16x32_bf16 v[18:21], v[188:191], v[222:225], v[18:21]
	v_mfma_f32_16x16x32_bf16 v[6:9], v[180:183], v[236:239], v[6:9]
	v_mfma_f32_16x16x32_bf16 v[2:5], v[188:191], v[236:239], v[2:5]
	s_barrier
	s_setprio 1
	s_add_i32 s12, 0, 0x18000
	s_add_i32 s13, 0, 0x1c000
	ds_read_b128 v[160:163], v156 offset:32768
	ds_read_b128 v[164:167], v156 offset:33792
	ds_read_b128 v[168:171], v156 offset:34816
	ds_read_b128 v[172:175], v156 offset:35840
	ds_read_b128 v[176:179], v156 offset:49152
	ds_read_b128 v[180:183], v156 offset:50176
	ds_read_b128 v[184:187], v156 offset:51200
	ds_read_b128 v[188:191], v156 offset:52224
	s_add_u32 s10, s54, 0x100000
	s_addc_u32 s11, s55, 0
	s_mov_b32 m0, s67
	ds_read_b128 v[192:195], v159 offset:32768
	ds_read_b128 v[196:199], v159 offset:33792
	ds_read_b128 v[210:213], v159 offset:34816
	ds_read_b128 v[214:217], v159 offset:35840
	ds_read_b128 v[218:221], v159 offset:36864
	ds_read_b128 v[222:225], v159 offset:37888
	ds_read_b128 v[226:229], v159 offset:38912
	ds_read_b128 v[236:239], v159 offset:39936
	global_load_lds_dwordx4 v116, s[10:11]
	s_mov_b32 m0, s68
	s_nop 0
	global_load_lds_dwordx4 v138, s[10:11]
	s_waitcnt vmcnt(8)
	s_waitcnt lgkmcnt(0)
	s_setprio 0
	s_barrier
	v_mfma_f32_16x16x32_bf16 v[132:135], v[160:163], v[192:195], v[132:135]
	v_mfma_f32_16x16x32_bf16 v[128:131], v[168:171], v[192:195], v[128:131]
	v_mfma_f32_16x16x32_bf16 v[110:113], v[160:163], v[210:213], v[110:113]
	v_mfma_f32_16x16x32_bf16 v[106:109], v[168:171], v[210:213], v[106:109]
	v_mfma_f32_16x16x32_bf16 v[94:97], v[160:163], v[218:221], v[94:97]
	v_mfma_f32_16x16x32_bf16 v[90:93], v[168:171], v[218:221], v[90:93]
	v_mfma_f32_16x16x32_bf16 v[78:81], v[160:163], v[226:229], v[78:81]
	v_mfma_f32_16x16x32_bf16 v[74:77], v[168:171], v[226:229], v[74:77]
	v_mfma_f32_16x16x32_bf16 v[132:135], v[164:167], v[196:199], v[132:135]
	v_mfma_f32_16x16x32_bf16 v[128:131], v[172:175], v[196:199], v[128:131]
	v_mfma_f32_16x16x32_bf16 v[110:113], v[164:167], v[214:217], v[110:113]
	v_mfma_f32_16x16x32_bf16 v[106:109], v[172:175], v[214:217], v[106:109]
	v_mfma_f32_16x16x32_bf16 v[94:97], v[164:167], v[222:225], v[94:97]
	v_mfma_f32_16x16x32_bf16 v[90:93], v[172:175], v[222:225], v[90:93]
	v_mfma_f32_16x16x32_bf16 v[78:81], v[164:167], v[236:239], v[78:81]
	v_mfma_f32_16x16x32_bf16 v[74:77], v[172:175], v[236:239], v[74:77]
	v_mfma_f32_16x16x32_bf16 v[124:127], v[176:179], v[192:195], v[124:127]
	v_mfma_f32_16x16x32_bf16 v[120:123], v[184:187], v[192:195], v[120:123]
	v_mfma_f32_16x16x32_bf16 v[102:105], v[176:179], v[210:213], v[102:105]
	v_mfma_f32_16x16x32_bf16 v[98:101], v[184:187], v[210:213], v[98:101]
	v_mfma_f32_16x16x32_bf16 v[86:89], v[176:179], v[218:221], v[86:89]
	v_mfma_f32_16x16x32_bf16 v[82:85], v[184:187], v[218:221], v[82:85]
	v_mfma_f32_16x16x32_bf16 v[70:73], v[176:179], v[226:229], v[70:73]
	v_mfma_f32_16x16x32_bf16 v[66:69], v[184:187], v[226:229], v[66:69]
	v_mfma_f32_16x16x32_bf16 v[124:127], v[180:183], v[196:199], v[124:127]
	v_mfma_f32_16x16x32_bf16 v[120:123], v[188:191], v[196:199], v[120:123]
	v_mfma_f32_16x16x32_bf16 v[102:105], v[180:183], v[214:217], v[102:105]
	v_mfma_f32_16x16x32_bf16 v[98:101], v[188:191], v[214:217], v[98:101]
	v_mfma_f32_16x16x32_bf16 v[86:89], v[180:183], v[222:225], v[86:89]
	v_mfma_f32_16x16x32_bf16 v[82:85], v[188:191], v[222:225], v[82:85]
	v_mfma_f32_16x16x32_bf16 v[70:73], v[180:183], v[236:239], v[70:73]
	v_mfma_f32_16x16x32_bf16 v[66:69], v[188:191], v[236:239], v[66:69]
	s_barrier
	s_setprio 1
	s_add_i32 s10, s12, s64
	s_add_u32 s100, s52, s20
	s_addc_u32 s101, s53, s21
	s_mov_b32 m0, s10
	ds_read_b128 v[192:195], v159 offset:49152
	ds_read_b128 v[196:199], v159 offset:50176
	ds_read_b128 v[210:213], v159 offset:51200
	ds_read_b128 v[214:217], v159 offset:52224
	ds_read_b128 v[218:221], v159 offset:53248
	ds_read_b128 v[222:225], v159 offset:54272
	ds_read_b128 v[226:229], v159 offset:55296
	ds_read_b128 v[236:239], v159 offset:56320
	global_load_lds_dwordx4 v136, s[100:101]
	s_add_i32 m0, s10, 0x2000
	s_add_u32 s10, s52, 0x100080
	s_addc_u32 s11, s53, 0
	s_add_i32 s12, s13, s64
	global_load_lds_dwordx4 v140, s[100:101]
	s_mov_b32 m0, s12
	s_nop 0
	global_load_lds_dwordx4 v136, s[10:11]
	s_add_i32 m0, s12, 0x2000
	s_add_u32 s100, s54, s20
	s_addc_u32 s101, s55, s21
	global_load_lds_dwordx4 v140, s[10:11]
	s_mov_b32 m0, s71
	s_nop 0
	global_load_lds_dwordx4 v116, s[100:101]
	s_mov_b32 m0, s72
	s_nop 0
	global_load_lds_dwordx4 v138, s[100:101]
	s_waitcnt vmcnt(8)
	s_waitcnt lgkmcnt(0)
	s_setprio 0
	s_barrier
	v_mfma_f32_16x16x32_bf16 v[62:65], v[160:163], v[192:195], v[62:65]
	v_mfma_f32_16x16x32_bf16 v[58:61], v[168:171], v[192:195], v[58:61]
	v_mfma_f32_16x16x32_bf16 v[46:49], v[160:163], v[210:213], v[46:49]
	v_mfma_f32_16x16x32_bf16 v[42:45], v[168:171], v[210:213], v[42:45]
	v_mfma_f32_16x16x32_bf16 v[30:33], v[160:163], v[218:221], v[30:33]
	v_mfma_f32_16x16x32_bf16 v[26:29], v[168:171], v[218:221], v[26:29]
	v_mfma_f32_16x16x32_bf16 v[14:17], v[160:163], v[226:229], v[14:17]
	v_mfma_f32_16x16x32_bf16 v[10:13], v[168:171], v[226:229], v[10:13]
	v_mfma_f32_16x16x32_bf16 v[62:65], v[164:167], v[196:199], v[62:65]
	v_mfma_f32_16x16x32_bf16 v[58:61], v[172:175], v[196:199], v[58:61]
	v_mfma_f32_16x16x32_bf16 v[46:49], v[164:167], v[214:217], v[46:49]
	v_mfma_f32_16x16x32_bf16 v[42:45], v[172:175], v[214:217], v[42:45]
	v_mfma_f32_16x16x32_bf16 v[30:33], v[164:167], v[222:225], v[30:33]
	v_mfma_f32_16x16x32_bf16 v[26:29], v[172:175], v[222:225], v[26:29]
	v_mfma_f32_16x16x32_bf16 v[14:17], v[164:167], v[236:239], v[14:17]
	v_mfma_f32_16x16x32_bf16 v[10:13], v[172:175], v[236:239], v[10:13]
	v_mfma_f32_16x16x32_bf16 v[54:57], v[176:179], v[192:195], v[54:57]
	v_mfma_f32_16x16x32_bf16 v[50:53], v[184:187], v[192:195], v[50:53]
	v_mfma_f32_16x16x32_bf16 v[38:41], v[176:179], v[210:213], v[38:41]
	v_mfma_f32_16x16x32_bf16 v[34:37], v[184:187], v[210:213], v[34:37]
	v_mfma_f32_16x16x32_bf16 v[22:25], v[176:179], v[218:221], v[22:25]
	v_mfma_f32_16x16x32_bf16 v[18:21], v[184:187], v[218:221], v[18:21]
	v_mfma_f32_16x16x32_bf16 v[6:9], v[176:179], v[226:229], v[6:9]
	v_mfma_f32_16x16x32_bf16 v[2:5], v[184:187], v[226:229], v[2:5]
	v_mfma_f32_16x16x32_bf16 v[54:57], v[180:183], v[196:199], v[54:57]
	v_mfma_f32_16x16x32_bf16 v[50:53], v[188:191], v[196:199], v[50:53]
	v_mfma_f32_16x16x32_bf16 v[38:41], v[180:183], v[214:217], v[38:41]
	v_mfma_f32_16x16x32_bf16 v[34:37], v[188:191], v[214:217], v[34:37]
	v_mfma_f32_16x16x32_bf16 v[22:25], v[180:183], v[222:225], v[22:25]
	v_mfma_f32_16x16x32_bf16 v[18:21], v[188:191], v[222:225], v[18:21]
	v_mfma_f32_16x16x32_bf16 v[6:9], v[180:183], v[236:239], v[6:9]
	v_mfma_f32_16x16x32_bf16 v[2:5], v[188:191], v[236:239], v[2:5]
	s_barrier
	s_setprio 1
	s_add_i32 s9, s9, 2
	s_add_u32 s50, s50, 0x100
	s_addc_u32 s51, s51, 0
	s_add_u32 s7, s7, 0x100
	s_addc_u32 s8, s8, 0
	s_cmp_gt_u32 s9, 61
	s_cbranch_scc0 .LBB0_1166
	s_setprio 0
	s_and_b64 vcc, exec, s[30:31]
	s_cbranch_vccz .LBB0_1169
	s_barrier

.LBB0_1370:
	s_ashr_i32 s97, s96, 31
	s_lshl_b64 s[8:9], s[96:97], 23
	s_add_u32 s10, s89, s8
	s_addc_u32 s11, s87, s9
	s_ashr_i32 s67, s66, 31
	s_lshl_b64 s[8:9], s[66:67], 15
	s_add_u32 s74, s10, s8
	s_addc_u32 s75, s11, s9
	s_ashr_i32 s93, s92, 31
	s_lshl_b64 s[10:11], s[92:93], 23
	s_add_u32 s10, s71, s10
	s_addc_u32 s11, s70, s11
	s_add_u32 s76, s10, s8
	s_addc_u32 s77, s11, s9
	s_cmp_lt_i32 s68, 1
	s_cbranch_scc1 .LBB0_1373
	s_and_b64 s[8:9], s[72:73], exec
	s_cselect_b32 s8, s75, s91
	s_cselect_b32 s9, s74, s90
	s_cselect_b32 s10, s77, s31
	s_cselect_b32 s11, s76, s30
	s_add_i32 s12, s68, -2
	s_add_u32 s40, s90, 0xc000
	s_addc_u32 s41, s91, 0
	s_add_u32 s13, s30, 0x10000
	s_addc_u32 s14, s31, 0
	s_mov_b32 s16, 0
	v_add_u32_e32 v116, 0x10000, v119
	s_waitcnt lgkmcnt(0)
.LBB0_1372:
	s_add_i32 s15, s16, 2
	s_add_u32 s17, s40, 0x4000
	s_addc_u32 s18, s41, 0
	s_cmp_eq_u32 s12, s16
	s_cselect_b32 s82, s9, s17
	s_cselect_b32 s83, s8, s18
	s_cselect_b32 s80, s11, s13
	s_cselect_b32 s81, s10, s14
	s_add_u32 s78, s82, 0x8000
	s_addc_u32 s79, s83, 0
	s_add_i32 s16, 0, 0x10000
	s_add_i32 s18, 0, 0x14000
	ds_read_b128 v[136:139], v116
	ds_read_b128 v[140:143], v116 offset:1024
	ds_read_b128 v[170:173], v116 offset:2048
	ds_read_b128 v[174:177], v116 offset:3072
	ds_read_b128 v[178:181], v116 offset:16384
	ds_read_b128 v[182:185], v116 offset:17408
	ds_read_b128 v[186:189], v116 offset:18432
	ds_read_b128 v[190:193], v116 offset:19456
	s_add_i32 m0, s23, 0xc000
	ds_read_b128 v[194:197], v153
	ds_read_b128 v[210:213], v153 offset:1024
	ds_read_b128 v[214:217], v153 offset:2048
	ds_read_b128 v[218:221], v153 offset:3072
	ds_read_b128 v[222:225], v153 offset:4096
	ds_read_b128 v[226:229], v153 offset:5120
	ds_read_b128 v[236:239], v153 offset:6144
	ds_read_b128 v[240:243], v153 offset:7168
	global_load_lds_dwordx4 v166, s[40:41]
	s_add_i32 m0, s23, 0xe000
	s_nop 0
	global_load_lds_dwordx4 v168, s[40:41]
	s_waitcnt vmcnt(8)
	s_waitcnt lgkmcnt(0)
	s_setprio 0
	s_barrier
	v_mfma_f32_16x16x32_bf16 v[132:135], v[136:139], v[194:197], v[132:135]
	v_mfma_f32_16x16x32_bf16 v[128:131], v[170:173], v[194:197], v[128:131]
	v_mfma_f32_16x16x32_bf16 v[124:127], v[136:139], v[214:217], v[124:127]
	v_mfma_f32_16x16x32_bf16 v[120:123], v[170:173], v[214:217], v[120:123]
	v_mfma_f32_16x16x32_bf16 v[110:113], v[136:139], v[222:225], v[110:113]
	v_mfma_f32_16x16x32_bf16 v[106:109], v[170:173], v[222:225], v[106:109]
	v_mfma_f32_16x16x32_bf16 v[102:105], v[136:139], v[236:239], v[102:105]
	v_mfma_f32_16x16x32_bf16 v[98:101], v[170:173], v[236:239], v[98:101]
	v_mfma_f32_16x16x32_bf16 v[132:135], v[140:143], v[210:213], v[132:135]
	v_mfma_f32_16x16x32_bf16 v[128:131], v[174:177], v[210:213], v[128:131]
	v_mfma_f32_16x16x32_bf16 v[124:127], v[140:143], v[218:221], v[124:127]
	v_mfma_f32_16x16x32_bf16 v[120:123], v[174:177], v[218:221], v[120:123]
	v_mfma_f32_16x16x32_bf16 v[110:113], v[140:143], v[226:229], v[110:113]
	v_mfma_f32_16x16x32_bf16 v[106:109], v[174:177], v[226:229], v[106:109]
	v_mfma_f32_16x16x32_bf16 v[102:105], v[140:143], v[240:243], v[102:105]
	v_mfma_f32_16x16x32_bf16 v[98:101], v[174:177], v[240:243], v[98:101]
	v_mfma_f32_16x16x32_bf16 v[94:97], v[178:181], v[194:197], v[94:97]
	v_mfma_f32_16x16x32_bf16 v[90:93], v[186:189], v[194:197], v[90:93]
	v_mfma_f32_16x16x32_bf16 v[86:89], v[178:181], v[214:217], v[86:89]
	v_mfma_f32_16x16x32_bf16 v[82:85], v[186:189], v[214:217], v[82:85]
	v_mfma_f32_16x16x32_bf16 v[78:81], v[178:181], v[222:225], v[78:81]
	v_mfma_f32_16x16x32_bf16 v[74:77], v[186:189], v[222:225], v[74:77]
	v_mfma_f32_16x16x32_bf16 v[66:69], v[178:181], v[236:239], v[66:69]
	v_mfma_f32_16x16x32_bf16 v[58:61], v[186:189], v[236:239], v[58:61]
	v_mfma_f32_16x16x32_bf16 v[94:97], v[182:185], v[210:213], v[94:97]
	v_mfma_f32_16x16x32_bf16 v[90:93], v[190:193], v[210:213], v[90:93]
	v_mfma_f32_16x16x32_bf16 v[86:89], v[182:185], v[218:221], v[86:89]
	v_mfma_f32_16x16x32_bf16 v[82:85], v[190:193], v[218:221], v[82:85]
	v_mfma_f32_16x16x32_bf16 v[78:81], v[182:185], v[226:229], v[78:81]
	v_mfma_f32_16x16x32_bf16 v[74:77], v[190:193], v[226:229], v[74:77]
	v_mfma_f32_16x16x32_bf16 v[66:69], v[182:185], v[240:243], v[66:69]
	v_mfma_f32_16x16x32_bf16 v[58:61], v[190:193], v[240:243], v[58:61]
	s_barrier
	s_setprio 1
	s_add_i32 s16, s16, s59
	s_mov_b32 m0, s16
	ds_read_b128 v[194:197], v153 offset:16384
	ds_read_b128 v[210:213], v153 offset:17408
	ds_read_b128 v[214:217], v153 offset:18432
	ds_read_b128 v[218:221], v153 offset:19456
	ds_read_b128 v[222:225], v153 offset:20480
	ds_read_b128 v[226:229], v153 offset:21504
	ds_read_b128 v[236:239], v153 offset:22528
	ds_read_b128 v[240:243], v153 offset:23552
	global_load_lds_dwordx4 v158, s[80:81]
	s_add_i32 m0, s16, 0x2000
	s_add_u32 s16, s80, 0x4000
	s_addc_u32 s17, s81, 0
	s_add_i32 s18, s18, s59
	global_load_lds_dwordx4 v162, s[80:81]
	s_mov_b32 m0, s18
	s_nop 0
	global_load_lds_dwordx4 v158, s[16:17]
	s_add_i32 m0, s18, 0x2000
	s_nop 0
	global_load_lds_dwordx4 v162, s[16:17]
	s_mov_b32 m0, s23
	s_nop 0
	global_load_lds_dwordx4 v156, s[82:83]
	s_mov_b32 m0, s25
	s_nop 0
	global_load_lds_dwordx4 v160, s[82:83]
	s_waitcnt vmcnt(8)
	s_waitcnt lgkmcnt(0)
	s_setprio 0
	s_barrier
	v_mfma_f32_16x16x32_bf16 v[70:73], v[136:139], v[194:197], v[70:73]
	v_mfma_f32_16x16x32_bf16 v[62:65], v[170:173], v[194:197], v[62:65]
	v_mfma_f32_16x16x32_bf16 v[54:57], v[136:139], v[214:217], v[54:57]
	v_mfma_f32_16x16x32_bf16 v[50:53], v[170:173], v[214:217], v[50:53]
	v_mfma_f32_16x16x32_bf16 v[46:49], v[136:139], v[222:225], v[46:49]
	v_mfma_f32_16x16x32_bf16 v[42:45], v[170:173], v[222:225], v[42:45]
	v_mfma_f32_16x16x32_bf16 v[38:41], v[136:139], v[236:239], v[38:41]
	v_mfma_f32_16x16x32_bf16 v[34:37], v[170:173], v[236:239], v[34:37]
	v_mfma_f32_16x16x32_bf16 v[70:73], v[140:143], v[210:213], v[70:73]
	v_mfma_f32_16x16x32_bf16 v[62:65], v[174:177], v[210:213], v[62:65]
	v_mfma_f32_16x16x32_bf16 v[54:57], v[140:143], v[218:221], v[54:57]
	v_mfma_f32_16x16x32_bf16 v[50:53], v[174:177], v[218:221], v[50:53]
	v_mfma_f32_16x16x32_bf16 v[46:49], v[140:143], v[226:229], v[46:49]
	v_mfma_f32_16x16x32_bf16 v[42:45], v[174:177], v[226:229], v[42:45]
	v_mfma_f32_16x16x32_bf16 v[38:41], v[140:143], v[240:243], v[38:41]
	v_mfma_f32_16x16x32_bf16 v[34:37], v[174:177], v[240:243], v[34:37]
	v_mfma_f32_16x16x32_bf16 v[30:33], v[178:181], v[194:197], v[30:33]
	v_mfma_f32_16x16x32_bf16 v[26:29], v[186:189], v[194:197], v[26:29]
	v_mfma_f32_16x16x32_bf16 v[22:25], v[178:181], v[214:217], v[22:25]
	v_mfma_f32_16x16x32_bf16 v[18:21], v[186:189], v[214:217], v[18:21]
	v_mfma_f32_16x16x32_bf16 v[14:17], v[178:181], v[222:225], v[14:17]
	v_mfma_f32_16x16x32_bf16 v[10:13], v[186:189], v[222:225], v[10:13]
	v_mfma_f32_16x16x32_bf16 v[6:9], v[178:181], v[236:239], v[6:9]
	v_mfma_f32_16x16x32_bf16 v[2:5], v[186:189], v[236:239], v[2:5]
	v_mfma_f32_16x16x32_bf16 v[30:33], v[182:185], v[210:213], v[30:33]
	v_mfma_f32_16x16x32_bf16 v[26:29], v[190:193], v[210:213], v[26:29]
	v_mfma_f32_16x16x32_bf16 v[22:25], v[182:185], v[218:221], v[22:25]
	v_mfma_f32_16x16x32_bf16 v[18:21], v[190:193], v[218:221], v[18:21]
	v_mfma_f32_16x16x32_bf16 v[14:17], v[182:185], v[226:229], v[14:17]
	v_mfma_f32_16x16x32_bf16 v[10:13], v[190:193], v[226:229], v[10:13]
	v_mfma_f32_16x16x32_bf16 v[6:9], v[182:185], v[240:243], v[6:9]
	v_mfma_f32_16x16x32_bf16 v[2:5], v[190:193], v[240:243], v[2:5]
	s_barrier
	s_setprio 1
	s_add_i32 s18, 0, 0x18000
	s_add_i32 s19, 0, 0x1c000
	ds_read_b128 v[136:139], v116 offset:32768
	ds_read_b128 v[140:143], v116 offset:33792
	ds_read_b128 v[170:173], v116 offset:34816
	ds_read_b128 v[174:177], v116 offset:35840
	ds_read_b128 v[178:181], v116 offset:49152
	ds_read_b128 v[182:185], v116 offset:50176
	ds_read_b128 v[186:189], v116 offset:51200
	ds_read_b128 v[190:193], v116 offset:52224
	s_add_u32 s16, s82, 0x4000
	s_addc_u32 s17, s83, 0
	s_mov_b32 m0, s42
	ds_read_b128 v[194:197], v153 offset:32768
	ds_read_b128 v[210:213], v153 offset:33792
	ds_read_b128 v[214:217], v153 offset:34816
	ds_read_b128 v[218:221], v153 offset:35840
	ds_read_b128 v[222:225], v153 offset:36864
	ds_read_b128 v[226:229], v153 offset:37888
	ds_read_b128 v[236:239], v153 offset:38912
	ds_read_b128 v[240:243], v153 offset:39936
	global_load_lds_dwordx4 v156, s[16:17]
	s_mov_b32 m0, s43
	s_nop 0
	global_load_lds_dwordx4 v160, s[16:17]
	s_waitcnt vmcnt(8)
	s_waitcnt lgkmcnt(0)
	s_setprio 0
	s_barrier
	v_mfma_f32_16x16x32_bf16 v[132:135], v[136:139], v[194:197], v[132:135]
	v_mfma_f32_16x16x32_bf16 v[128:131], v[170:173], v[194:197], v[128:131]
	v_mfma_f32_16x16x32_bf16 v[124:127], v[136:139], v[214:217], v[124:127]
	v_mfma_f32_16x16x32_bf16 v[120:123], v[170:173], v[214:217], v[120:123]
	v_mfma_f32_16x16x32_bf16 v[110:113], v[136:139], v[222:225], v[110:113]
	v_mfma_f32_16x16x32_bf16 v[106:109], v[170:173], v[222:225], v[106:109]
	v_mfma_f32_16x16x32_bf16 v[102:105], v[136:139], v[236:239], v[102:105]
	v_mfma_f32_16x16x32_bf16 v[98:101], v[170:173], v[236:239], v[98:101]
	v_mfma_f32_16x16x32_bf16 v[132:135], v[140:143], v[210:213], v[132:135]
	v_mfma_f32_16x16x32_bf16 v[128:131], v[174:177], v[210:213], v[128:131]
	v_mfma_f32_16x16x32_bf16 v[124:127], v[140:143], v[218:221], v[124:127]
	v_mfma_f32_16x16x32_bf16 v[120:123], v[174:177], v[218:221], v[120:123]
	v_mfma_f32_16x16x32_bf16 v[110:113], v[140:143], v[226:229], v[110:113]
	v_mfma_f32_16x16x32_bf16 v[106:109], v[174:177], v[226:229], v[106:109]
	v_mfma_f32_16x16x32_bf16 v[102:105], v[140:143], v[240:243], v[102:105]
	v_mfma_f32_16x16x32_bf16 v[98:101], v[174:177], v[240:243], v[98:101]
	v_mfma_f32_16x16x32_bf16 v[94:97], v[178:181], v[194:197], v[94:97]
	v_mfma_f32_16x16x32_bf16 v[90:93], v[186:189], v[194:197], v[90:93]
	v_mfma_f32_16x16x32_bf16 v[86:89], v[178:181], v[214:217], v[86:89]
	v_mfma_f32_16x16x32_bf16 v[82:85], v[186:189], v[214:217], v[82:85]
	v_mfma_f32_16x16x32_bf16 v[78:81], v[178:181], v[222:225], v[78:81]
	v_mfma_f32_16x16x32_bf16 v[74:77], v[186:189], v[222:225], v[74:77]
	v_mfma_f32_16x16x32_bf16 v[66:69], v[178:181], v[236:239], v[66:69]
	v_mfma_f32_16x16x32_bf16 v[58:61], v[186:189], v[236:239], v[58:61]
	v_mfma_f32_16x16x32_bf16 v[94:97], v[182:185], v[210:213], v[94:97]
	v_mfma_f32_16x16x32_bf16 v[90:93], v[190:193], v[210:213], v[90:93]
	v_mfma_f32_16x16x32_bf16 v[86:89], v[182:185], v[218:221], v[86:89]
	v_mfma_f32_16x16x32_bf16 v[82:85], v[190:193], v[218:221], v[82:85]
	v_mfma_f32_16x16x32_bf16 v[78:81], v[182:185], v[226:229], v[78:81]
	v_mfma_f32_16x16x32_bf16 v[74:77], v[190:193], v[226:229], v[74:77]
	v_mfma_f32_16x16x32_bf16 v[66:69], v[182:185], v[240:243], v[66:69]
	v_mfma_f32_16x16x32_bf16 v[58:61], v[190:193], v[240:243], v[58:61]
	s_barrier
	s_setprio 1
	s_add_u32 s16, s80, 0x8000
	s_addc_u32 s17, s81, 0
	s_add_i32 s18, s18, s59
	s_mov_b32 m0, s18
	ds_read_b128 v[194:197], v153 offset:49152
	ds_read_b128 v[210:213], v153 offset:50176
	ds_read_b128 v[214:217], v153 offset:51200
	ds_read_b128 v[218:221], v153 offset:52224
	ds_read_b128 v[222:225], v153 offset:53248
	ds_read_b128 v[226:229], v153 offset:54272
	ds_read_b128 v[236:239], v153 offset:55296
	ds_read_b128 v[240:243], v153 offset:56320
	global_load_lds_dwordx4 v158, s[16:17]
	s_add_i32 m0, s18, 0x2000
	s_add_i32 s18, s19, s59
	global_load_lds_dwordx4 v162, s[16:17]
	s_add_u32 s16, s80, 0xc000
	s_addc_u32 s17, s81, 0
	s_mov_b32 m0, s18
	s_nop 0
	global_load_lds_dwordx4 v158, s[16:17]
	s_add_i32 m0, s18, 0x2000
	s_nop 0
	global_load_lds_dwordx4 v162, s[16:17]
	s_mov_b32 m0, s53
	s_nop 0
	global_load_lds_dwordx4 v156, s[78:79]
	s_mov_b32 m0, s52
	s_nop 0
	global_load_lds_dwordx4 v160, s[78:79]
	s_waitcnt vmcnt(8)
	s_waitcnt lgkmcnt(0)
	s_setprio 0
	s_barrier
	v_mfma_f32_16x16x32_bf16 v[70:73], v[136:139], v[194:197], v[70:73]
	v_mfma_f32_16x16x32_bf16 v[62:65], v[170:173], v[194:197], v[62:65]
	v_mfma_f32_16x16x32_bf16 v[54:57], v[136:139], v[214:217], v[54:57]
	v_mfma_f32_16x16x32_bf16 v[50:53], v[170:173], v[214:217], v[50:53]
	v_mfma_f32_16x16x32_bf16 v[46:49], v[136:139], v[222:225], v[46:49]
	v_mfma_f32_16x16x32_bf16 v[42:45], v[170:173], v[222:225], v[42:45]
	v_mfma_f32_16x16x32_bf16 v[38:41], v[136:139], v[236:239], v[38:41]
	v_mfma_f32_16x16x32_bf16 v[34:37], v[170:173], v[236:239], v[34:37]
	v_mfma_f32_16x16x32_bf16 v[70:73], v[140:143], v[210:213], v[70:73]
	v_mfma_f32_16x16x32_bf16 v[62:65], v[174:177], v[210:213], v[62:65]
	v_mfma_f32_16x16x32_bf16 v[54:57], v[140:143], v[218:221], v[54:57]
	v_mfma_f32_16x16x32_bf16 v[50:53], v[174:177], v[218:221], v[50:53]
	v_mfma_f32_16x16x32_bf16 v[46:49], v[140:143], v[226:229], v[46:49]
	v_mfma_f32_16x16x32_bf16 v[42:45], v[174:177], v[226:229], v[42:45]
	v_mfma_f32_16x16x32_bf16 v[38:41], v[140:143], v[240:243], v[38:41]
	v_mfma_f32_16x16x32_bf16 v[34:37], v[174:177], v[240:243], v[34:37]
	v_mfma_f32_16x16x32_bf16 v[30:33], v[178:181], v[194:197], v[30:33]
	v_mfma_f32_16x16x32_bf16 v[26:29], v[186:189], v[194:197], v[26:29]
	v_mfma_f32_16x16x32_bf16 v[22:25], v[178:181], v[214:217], v[22:25]
	v_mfma_f32_16x16x32_bf16 v[18:21], v[186:189], v[214:217], v[18:21]
	v_mfma_f32_16x16x32_bf16 v[14:17], v[178:181], v[222:225], v[14:17]
	v_mfma_f32_16x16x32_bf16 v[10:13], v[186:189], v[222:225], v[10:13]
	v_mfma_f32_16x16x32_bf16 v[6:9], v[178:181], v[236:239], v[6:9]
	v_mfma_f32_16x16x32_bf16 v[2:5], v[186:189], v[236:239], v[2:5]
	v_mfma_f32_16x16x32_bf16 v[30:33], v[182:185], v[210:213], v[30:33]
	v_mfma_f32_16x16x32_bf16 v[26:29], v[190:193], v[210:213], v[26:29]
	v_mfma_f32_16x16x32_bf16 v[22:25], v[182:185], v[218:221], v[22:25]
	v_mfma_f32_16x16x32_bf16 v[18:21], v[190:193], v[218:221], v[18:21]
	v_mfma_f32_16x16x32_bf16 v[14:17], v[182:185], v[226:229], v[14:17]
	v_mfma_f32_16x16x32_bf16 v[10:13], v[190:193], v[226:229], v[10:13]
	v_mfma_f32_16x16x32_bf16 v[6:9], v[182:185], v[240:243], v[6:9]
	v_mfma_f32_16x16x32_bf16 v[2:5], v[190:193], v[240:243], v[2:5]
	s_barrier
	s_setprio 1
	s_add_u32 s40, s40, 0x10000
	s_addc_u32 s41, s41, 0
	s_add_u32 s13, s13, 0x10000
	s_addc_u32 s14, s14, 0
	s_cmp_ge_i32 s15, s68
	s_mov_b32 s16, s15
	s_cbranch_scc0 .LBB0_1372
	s_setprio 0

	.amdhsa_kernel _Z9hymba_fwd4Args
		.amdhsa_group_segment_fixed_size 0
		.amdhsa_private_segment_fixed_size 0
		.amdhsa_kernarg_size 448
		.amdhsa_user_sgpr_count 2
		.amdhsa_user_sgpr_dispatch_ptr 0
		.amdhsa_user_sgpr_queue_ptr 0
		.amdhsa_user_sgpr_kernarg_segment_ptr 1
		.amdhsa_user_sgpr_dispatch_id 0
		.amdhsa_user_sgpr_kernarg_preload_length 0
		.amdhsa_user_sgpr_kernarg_preload_offset 0
		.amdhsa_user_sgpr_private_segment_size 0
		.amdhsa_uses_dynamic_stack 0
		.amdhsa_enable_private_segment 0
		.amdhsa_system_sgpr_workgroup_id_x 1
		.amdhsa_system_sgpr_workgroup_id_y 0
		.amdhsa_system_sgpr_workgroup_id_z 0
		.amdhsa_system_sgpr_workgroup_info 0
		.amdhsa_system_vgpr_workitem_id 0
		.amdhsa_next_free_vgpr 256
		.amdhsa_next_free_sgpr 102
		.amdhsa_accum_offset 256
		.amdhsa_reserve_vcc 1
		.amdhsa_float_round_mode_32 0
		.amdhsa_float_round_mode_16_64 0
		.amdhsa_float_denorm_mode_32 3
		.amdhsa_float_denorm_mode_16_64 3
		.amdhsa_dx10_clamp 1
		.amdhsa_ieee_mode 1
		.amdhsa_fp16_overflow 0
		.amdhsa_tg_split 0
		.amdhsa_exception_fp_ieee_invalid_op 0
		.amdhsa_exception_fp_denorm_src 0
		.amdhsa_exception_fp_ieee_div_zero 0
		.amdhsa_exception_fp_ieee_overflow 0
		.amdhsa_exception_fp_ieee_underflow 0
		.amdhsa_exception_fp_ieee_inexact 0
		.amdhsa_exception_int_div_zero 0
	.end_amdhsa_kernel

.Lfunc_end0:
	.size	_Z9hymba_fwd4Args, .Lfunc_end0-_Z9hymba_fwd4Args
	.set _Z9hymba_fwd4Args.num_vgpr, 256
	.set _Z9hymba_fwd4Args.num_agpr, 0
	.set _Z9hymba_fwd4Args.numbered_sgpr, 102
	.set _Z9hymba_fwd4Args.num_named_barrier, 0
	.set _Z9hymba_fwd4Args.private_seg_size, 0
	.set _Z9hymba_fwd4Args.uses_vcc, 1
	.set _Z9hymba_fwd4Args.uses_flat_scratch, 0
	.set _Z9hymba_fwd4Args.has_dyn_sized_stack, 0
	.set _Z9hymba_fwd4Args.has_recursion, 0
	.set _Z9hymba_fwd4Args.has_indirect_call, 0

amdhsa.kernels:
  - .agpr_count:     0
    .args:
      - .offset:         0
        .size:           192
        .value_kind:     by_value
      - .offset:         192
        .size:           4
        .value_kind:     hidden_block_count_x
      - .offset:         196
        .size:           4
        .value_kind:     hidden_block_count_y
      - .offset:         200
        .size:           4
        .value_kind:     hidden_block_count_z
      - .offset:         204
        .size:           2
        .value_kind:     hidden_group_size_x
      - .offset:         206
        .size:           2
        .value_kind:     hidden_group_size_y
      - .offset:         208
        .size:           2
        .value_kind:     hidden_group_size_z
      - .offset:         210
        .size:           2
        .value_kind:     hidden_remainder_x
      - .offset:         212
        .size:           2
        .value_kind:     hidden_remainder_y
      - .offset:         214
        .size:           2
        .value_kind:     hidden_remainder_z
      - .offset:         232
        .size:           8
        .value_kind:     hidden_global_offset_x
      - .offset:         240
        .size:           8
        .value_kind:     hidden_global_offset_y
      - .offset:         248
        .size:           8
        .value_kind:     hidden_global_offset_z
      - .offset:         256
        .size:           2
        .value_kind:     hidden_grid_dims
      - .offset:         312
        .size:           4
        .value_kind:     hidden_dynamic_lds_size
    .group_segment_fixed_size: 0
    .kernarg_segment_align: 8
    .kernarg_segment_size: 448
    .language:       OpenCL C
    .language_version:
      - 2
      - 0
    .max_flat_workgroup_size: 512
    .name:           _Z9hymba_fwd4Args
    .private_segment_fixed_size: 0
    .sgpr_count:     108
    .sgpr_spill_count: 308
    .symbol:         _Z9hymba_fwd4Args.kd
    .uniform_work_group_size: 1
    .uses_dynamic_stack: false
    .vgpr_count:     256
    .vgpr_spill_count: 0
    .wavefront_size: 64
